# conv gate_b epilogue: U rows staged once per column half into LDS by DMA; per-iteration global loads become ds_reads
# speedup vs baseline: 1.1057x; 1.0052x over previous
; __device__ __forceinline__ void row_rs8(const float* ssq, int row0, int fq, float (&rr)[2][4]) {
;     float v[2][4][4];
; #pragma unroll
;     for (int ai = 0; ai < 2; ++ai)
; #pragma unroll
;         for (int m = 0; m < 4; ++m) { const float* p = ssq + (size_t)(4 * fq) * 16384 + row0 + ai * HALF + m * 16;
; #pragma unroll
;             for (int k = 0; k < 4; ++k) v[ai][m][k] = ld_agent(p + k * 16384); }
; #pragma unroll
;     for (int ai = 0; ai < 2; ++ai)
; #pragma unroll
;         for (int m = 0; m < 4; ++m) { float s = (v[ai][m][0] + v[ai][m][1]) + (v[ai][m][2] + v[ai][m][3]);
;             s += __shfl_xor(s, 16); s += __shfl_xor(s, 32); rr[ai][m] = __builtin_amdgcn_rsqf(s * (1.0f / 1024.0f) + RMS_EPS); }
;     __device__ __forceinline__ void operator()(const f32x4 (&acc)[2][2][4][2], const Unit& u, int wr, int wc, int fr, int fq) const {
;     ...
;             asm volatile("s_waitcnt vmcnt(0)" ::: "memory");
; #pragma unroll
;             for (int bj = 0; bj < 2; ++bj) {
;                 const int col = (u.pn - 8) * BM + bj * HALF + wc * 32 + 8 * fq;
;                 const f32x4 k0a = *(const f32x4*)(taps + col), k0b = *(const f32x4*)(taps + col + 4), k1a = *(const f32x4*)(taps + 1024 + col), k1b = *(const f32x4*)(taps + 1024 + col + 4),
.LBB0_291:
	v_mov_b32_e32 v130, v248
	v_readlane_b32 s6, v255, 4
	v_readlane_b32 s8, v252, 21
	v_readlane_b32 s9, v252, 22
	v_add_u32_e32 v155, s6, v130
	v_lshl_add_u32 v202, s3, 8, v155
	v_ashrrev_i32_e32 v203, 31, v202
	v_lshl_add_u64 v[130:131], v[202:203], 2, v[178:179]
	s_mov_b32 s6, 0x10000
	v_add_co_u32_e32 v132, vcc, s6, v130
	s_mov_b32 s6, 0x20000
	s_nop 0
	v_addc_co_u32_e32 v133, vcc, 0, v131, vcc
	v_add_co_u32_e32 v134, vcc, s6, v130
	s_mov_b32 s6, 0x30000
	s_nop 0
	v_addc_co_u32_e32 v135, vcc, 0, v131, vcc
	v_add_co_u32_e32 v136, vcc, s6, v130
	s_mov_b64 s[6:7], -1
	s_nop 0
	v_addc_co_u32_e32 v137, vcc, 0, v131, vcc
	global_load_dword v138, v[132:133], off
	global_load_dword v139, v[132:133], off offset:64
	global_load_dword v140, v[132:133], off offset:128
	global_load_dword v141, v[134:135], off
	global_load_dword v142, v[134:135], off offset:64
	global_load_dword v143, v[134:135], off offset:128
	global_load_dword v144, v[134:135], off offset:192
	global_load_dword v145, v[136:137], off
	global_load_dword v146, v[136:137], off offset:64
	global_load_dword v147, v[136:137], off offset:128
	global_load_dword v148, v[136:137], off offset:192
	global_load_dword v149, v[136:137], off offset:512
	global_load_dword v150, v[130:131], off
	global_load_dword v151, v[130:131], off offset:64
	global_load_dword v152, v[130:131], off offset:128
	global_load_dword v153, v[130:131], off offset:192
	global_load_dword v154, v[130:131], off offset:512
	global_load_dword v156, v[130:131], off offset:576
	global_load_dword v157, v[132:133], off offset:192
	global_load_dword v158, v[132:133], off offset:512
	global_load_dword v159, v[132:133], off offset:576
	global_load_dword v160, v[134:135], off offset:512
	global_load_dword v161, v[134:135], off offset:576
	global_load_dword v162, v[136:137], off offset:576
	global_load_dword v163, v[130:131], off offset:640
	global_load_dword v164, v[132:133], off offset:640
	global_load_dword v165, v[134:135], off offset:640
	global_load_dword v168, v[136:137], off offset:640
	s_nop 0
	global_load_dword v130, v[130:131], off offset:704
	s_nop 0
	global_load_dword v131, v[132:133], off offset:704
	s_nop 0
	global_load_dword v132, v[134:135], off offset:704
	global_load_dword v133, v[136:137], off offset:704
	v_and_b32_e32 v135, 64, v242
	v_xor_b32_e32 v134, 16, v242
	v_add_u32_e32 v135, 64, v135
	v_xor_b32_e32 v136, 32, v242
	v_cmp_lt_i32_e32 vcc, v134, v135
	s_cmp_gt_i32 s37, 7
	s_waitcnt vmcnt(0)
	v_add_f32_e32 v137, v141, v145
	v_cndmask_b32_e32 v134, v242, v134, vcc
	v_cmp_lt_i32_e32 vcc, v136, v135
	v_add_f32_e32 v141, v143, v147
	v_lshlrev_b32_e32 v134, 2, v134
	v_cndmask_b32_e32 v135, v242, v136, vcc
	v_add_f32_e32 v136, v150, v138
	v_add_f32_e32 v138, v151, v139
	v_add_f32_e32 v139, v142, v146
	v_add_f32_e32 v140, v152, v140
	v_add_f32_e32 v143, v144, v148
	v_add_f32_e32 v142, v153, v157
	v_add_f32_e32 v136, v136, v137
	v_add_f32_e32 v137, v138, v139
	v_add_f32_e32 v138, v140, v141
	v_add_f32_e32 v144, v154, v158
	v_add_f32_e32 v145, v160, v149
	v_add_f32_e32 v139, v142, v143
	ds_bpermute_b32 v143, v134, v138
	v_add_f32_e32 v140, v144, v145
	ds_bpermute_b32 v141, v134, v136
	ds_bpermute_b32 v142, v134, v137
	ds_bpermute_b32 v144, v134, v139
	ds_bpermute_b32 v145, v134, v140
	v_lshlrev_b32_e32 v135, 2, v135
	s_waitcnt lgkmcnt(0)
	v_add_f32_e32 v138, v138, v143
	v_add_f32_e32 v136, v136, v141
	ds_bpermute_b32 v143, v135, v138
	v_add_f32_e32 v137, v137, v142
	v_add_f32_e32 v139, v139, v144
	v_add_f32_e32 v140, v140, v145
	ds_bpermute_b32 v141, v135, v136
	ds_bpermute_b32 v142, v135, v137
	ds_bpermute_b32 v144, v135, v139
	ds_bpermute_b32 v145, v135, v140
	s_waitcnt lgkmcnt(4)
	v_add_f32_e32 v138, v138, v143
	s_waitcnt lgkmcnt(3)
	v_add_f32_e32 v136, v136, v141
	v_fmamk_f32 v138, v138, 0x3a800000, v1
	v_add_f32_e32 v146, v156, v159
	v_add_f32_e32 v147, v161, v162
	s_waitcnt lgkmcnt(2)
	v_add_f32_e32 v137, v137, v142
	s_waitcnt lgkmcnt(1)
	v_add_f32_e32 v139, v139, v144
	v_fmamk_f32 v136, v136, 0x3a800000, v1
	v_rsq_f32_e32 v192, v138
	s_waitcnt lgkmcnt(0)
	v_add_f32_e32 v138, v140, v145
	v_fmamk_f32 v137, v137, 0x3a800000, v1
	v_fmamk_f32 v139, v139, 0x3a800000, v1
	v_rsq_f32_e32 v198, v136
	v_add_f32_e32 v136, v146, v147
	v_fmamk_f32 v138, v138, 0x3a800000, v1
	v_rsq_f32_e32 v196, v137
	ds_bpermute_b32 v137, v134, v136
	v_rsq_f32_e32 v194, v139
	v_rsq_f32_e32 v190, v138
	v_add_f32_e32 v138, v163, v164
	v_add_f32_e32 v139, v165, v168
	v_add_f32_e32 v130, v130, v131
	v_add_f32_e32 v131, v132, v133
	v_add_f32_e32 v138, v138, v139
	v_add_f32_e32 v130, v130, v131
	ds_bpermute_b32 v139, v134, v138
	ds_bpermute_b32 v131, v134, v130
	s_waitcnt lgkmcnt(2)
	v_add_f32_e32 v136, v136, v137
	ds_bpermute_b32 v137, v135, v136
	s_waitcnt lgkmcnt(2)
	v_add_f32_e32 v133, v138, v139
	s_waitcnt lgkmcnt(1)
	v_add_f32_e32 v130, v130, v131
	ds_bpermute_b32 v134, v135, v133
	ds_bpermute_b32 v131, v135, v130
	s_waitcnt lgkmcnt(2)
	v_add_f32_e32 v132, v136, v137
	v_fmamk_f32 v132, v132, 0x3a800000, v1
	v_rsq_f32_e32 v188, v132
	s_waitcnt lgkmcnt(1)
	v_add_f32_e32 v132, v133, v134
	s_waitcnt lgkmcnt(0)
	v_add_f32_e32 v130, v130, v131
	v_fmamk_f32 v132, v132, 0x3a800000, v1
	v_fmamk_f32 v130, v130, 0x3a800000, v1
	v_rsq_f32_e32 v186, v132
	v_rsq_f32_e32 v184, v130
	v_lshlrev_b64 v[130:131], 11, v[202:203]
	v_lshl_add_u64 v[200:201], s[8:9], 0, v[130:131]
	s_cbranch_scc0 .LBB0_421
	s_lshl_b32 s76, s37, 8
	v_or_b32_e32 v130, 0xfffff800, v250
	v_add_u32_e32 v206, s76, v130
	v_ashrrev_i32_e32 v207, 31, v206
	v_readlane_b32 s6, v255, 11
	v_lshlrev_b64 v[138:139], 2, v[206:207]
	v_readlane_b32 s7, v255, 12
	s_waitcnt vmcnt(0)
	s_barrier
;     __device__ __forceinline__ void operator()(const f32x4 (&acc)[2][2][4][2], const Unit& u, int wr, int wc, int fr, int fq) const {
;     ...
;             for (int bj = 0; bj < 2; ++bj) {
;                 const int col = (u.pn - 8) * BM + bj * HALF + wc * 32 + 8 * fq;
;                 const f32x4 k0a = *(const f32x4*)(taps + col), k0b = *(const f32x4*)(taps + col + 4), k1a = *(const f32x4*)(taps + 1024 + col), k1b = *(const f32x4*)(taps + 1024 + col + 4),
;                             k2a = *(const f32x4*)(taps + 2048 + col), k2b = *(const f32x4*)(taps + 2048 + col + 4);
; #pragma unroll
;                 for (int ai = 0; ai < 2; ++ai)
; #pragma unroll
;                     for (int m = 0; m < 4; ++m) { const int row = row0 + ai * HALF + m * 16, sq = row & 8191, lr = row & 255; const float r = rr[ai][m];
;                         const bool up_in = lr != 0, dn_in = lr != 255, up_halo = !up_in && sq != 0, dn_halo = !dn_in && sq != 8191;
;                         const bf16_t* up = U + (size_t)row * 1024 + col; const u32x4 z0 = {0u, 0u, 0u, 0u};
;                         const u32x4 uc = *(const u32x4*)up, ul = up_in ? *(const u32x4*)(up - 1024) : z0, ur = dn_in ? *(const u32x4*)(up + 1024) : z0;
;                         const f32x4 b0 = acc[ai][bj][m][0] * r, b1 = acc[ai][bj][m][1] * r;
;                         u32x4 w;
;                         w.x = cvt_pk_bf16(b0[0] * (k0a[0] * bf_lo(ul.x) + k1a[0] * bf_lo(uc.x) + k2a[0] * bf_lo(ur.x)), b0[1] * (k0a[1] * bf_hi(ul.x) + k1a[1] * bf_hi(uc.x) + k2a[1] * bf_hi(ur.x)));
;                         w.y = cvt_pk_bf16(b0[2] * (k0a[2] * bf_lo(ul.y) + k1a[2] * bf_lo(uc.y) + k2a[2] * bf_lo(ur.y)), b0[3] * (k0a[3] * bf_hi(ul.y) + k1a[3] * bf_hi(uc.y) + k2a[3] * bf_hi(ur.y)));
;                         w.z = cvt_pk_bf16(b1[0] * (k0b[0] * bf_lo(ul.z) + k1b[0] * bf_lo(uc.z) + k2b[0] * bf_lo(ur.z)), b1[1] * (k0b[1] * bf_hi(ul.z) + k1b[1] * bf_hi(uc.z) + k2b[1] * bf_hi(ur.z)));
;                         w.w = cvt_pk_bf16(b1[2] * (k0b[2] * bf_lo(ul.w) + k1b[2] * bf_lo(uc.w) + k2b[2] * bf_lo(ur.w)), b1[3] * (k0b[3] * bf_hi(ul.w) + k1b[3] * bf_hi(uc.w) + k2b[3] * bf_hi(ur.w)));
;                         if (up_halo || dn_halo) { const size_t ho = (size_t)(2 * u.pm + (dn_halo ? 1 : 0)) * 1024 + col;
	v_readfirstlane_b32 s101, v0
	s_lshr_b32 s101, s101, 6
	s_lshl_b32 s101, s101, 14
	v_and_b32_e32 v166, 63, v0
	v_lshrrev_b32_e32 v158, 4, v166
	v_and_b32_e32 v166, 15, v166
	v_lshlrev_b32_e32 v166, 6, v166
	v_lshl_add_u32 v166, v158, 4, v166
	v_add_u32_e32 v166, s101, v166
	v_lshl_add_u64 v[204:205], v[206:207], 1, v[200:201]
	v_mov_b32_e32 v154, 0
	v_lshl_add_u64 v[134:135], s[6:7], 0, v[138:139]
	v_readlane_b32 s6, v255, 9
	v_readlane_b32 s7, v255, 10
	global_load_dwordx4 v[130:133], v[134:135], off offset:16
	global_load_dwordx4 v[150:153], v[134:135], off
	v_lshl_add_u64 v[140:141], s[6:7], 0, v[138:139]
	v_readlane_b32 s6, v255, 13
	v_readlane_b32 s7, v255, 14
	global_load_dwordx4 v[134:137], v[140:141], off offset:16
	global_load_dwordx4 v[146:149], v[140:141], off
	v_lshl_add_u64 v[142:143], s[6:7], 0, v[138:139]
	global_load_dwordx4 v[138:141], v[142:143], off offset:16
	s_nop 0
	global_load_dwordx4 v[142:145], v[142:143], off
	v_cmp_eq_u32_sdwa s[10:11], v155, v167 src0_sel:BYTE_0 src1_sel:DWORD
	v_and_b32_e32 v158, 63, v0
	v_and_b32_e32 v159, 15, v158
	v_lshrrev_b32_e32 v160, 4, v158
	v_lshrrev_b32_e32 v161, 2, v159
	v_lshl_add_u32 v161, v160, 2, v161
	v_sub_u32_e32 v161, v161, v159
	v_add_u32_e32 v161, -1, v161
	v_lshlrev_b32_e32 v161, 11, v161
	v_and_b32_e32 v159, 3, v159
	v_sub_u32_e32 v159, v159, v160
	v_lshl_add_u32 v162, v159, 4, v161
	v_ashrrev_i32_e32 v163, 31, v162
	v_lshl_add_u64 v[162:163], v[204:205], 0, v[162:163]
	v_lshrrev_b32_e32 v160, 3, v158
	v_min_u32_e32 v160, 1, v160
	v_mul_u32_u24_e32 v160, 0x1f000, v160
	v_mov_b32_e32 v161, 0
	v_mov_b32_e32 v159, 0
	s_mov_b32 m0, s101
	s_nop 0
	global_load_lds_dwordx4 v[162:163], off
	s_add_i32 m0, s101, 0x400
	v_mov_b32_e32 v158, 0x8000
	v_lshl_add_u64 v[164:165], v[162:163], 0, v[158:159]
	global_load_lds_dwordx4 v[164:165], off
	s_add_i32 m0, s101, 0x800
	v_mov_b32_e32 v158, 0x10000
	v_lshl_add_u64 v[164:165], v[162:163], 0, v[158:159]
	global_load_lds_dwordx4 v[164:165], off
	s_add_i32 m0, s101, 0xc00
	v_mov_b32_e32 v158, 0x18000
	v_lshl_add_u64 v[164:165], v[162:163], 0, v[158:159]
	global_load_lds_dwordx4 v[164:165], off
	s_add_i32 m0, s101, 0x1000
	v_mov_b32_e32 v158, 0x20000
	v_lshl_add_u64 v[164:165], v[162:163], 0, v[158:159]
	v_lshl_add_u64 v[164:165], v[164:165], 0, v[160:161]
	global_load_lds_dwordx4 v[164:165], off
	s_add_i32 m0, s101, 0x1400
	v_mov_b32_e32 v158, 0x47000
	v_lshl_add_u64 v[164:165], v[162:163], 0, v[158:159]
	global_load_lds_dwordx4 v[164:165], off
	s_add_i32 m0, s101, 0x1800
	v_mov_b32_e32 v158, 0x4f000
	v_lshl_add_u64 v[164:165], v[162:163], 0, v[158:159]
	global_load_lds_dwordx4 v[164:165], off
	s_add_i32 m0, s101, 0x1c00
	v_mov_b32_e32 v158, 0x57000
	v_lshl_add_u64 v[164:165], v[162:163], 0, v[158:159]
	global_load_lds_dwordx4 v[164:165], off
	s_add_i32 m0, s101, 0x2000
	v_mov_b32_e32 v158, 0x5f000
	v_lshl_add_u64 v[164:165], v[162:163], 0, v[158:159]
	global_load_lds_dwordx4 v[164:165], off
	s_waitcnt vmcnt(0)
	s_barrier
	v_mov_b32_e32 v162, 0
	v_mov_b32_e32 v163, 0
	v_mov_b32_e32 v164, 0
	v_mov_b32_e32 v165, 0
	ds_read_b128 v[158:161], v166 offset:64
	v_cmp_ne_u32_sdwa s[6:7], v155, v167 src0_sel:BYTE_0 src1_sel:DWORD
	v_mov_b32_e32 v162, 0
	v_mov_b32_e32 v163, 0
	v_mov_b32_e32 v164, 0
	v_mov_b32_e32 v165, 0
	s_and_saveexec_b64 s[8:9], s[6:7]
	s_cbranch_execz .LBB0_294
	ds_read_b128 v[162:165], v166 offset:0
.LBB0_294:
	s_or_b64 exec, exec, s[8:9]
	s_movk_i32 s8, 0xff
	v_cmp_eq_u32_sdwa s[12:13], v155, s8 src0_sel:BYTE_0 src1_sel:DWORD
	v_cmp_ne_u32_sdwa s[8:9], v155, s8 src0_sel:BYTE_0 src1_sel:DWORD
	v_mov_b32_e32 v155, 0
	v_mov_b32_e32 v156, 0
	v_mov_b32_e32 v157, 0
	s_and_saveexec_b64 s[14:15], s[8:9]
	s_cbranch_execz .LBB0_296
	ds_read_b128 v[154:157], v166 offset:128
.LBB0_296:
	s_or_b64 exec, exec, s[14:15]
	s_waitcnt lgkmcnt(0)
	v_lshlrev_b32_e32 v216, 16, v162
	v_and_b32_e32 v217, 0xffff0000, v162
	v_lshlrev_b32_e32 v162, 16, v163
	v_and_b32_e32 v163, 0xffff0000, v163
	v_lshlrev_b32_e32 v218, 16, v158
	v_and_b32_e32 v219, 0xffff0000, v158
	v_pk_mul_f32 v[162:163], v[152:153], v[162:163]
	v_lshlrev_b32_e32 v158, 16, v159
	v_and_b32_e32 v159, 0xffff0000, v159
	v_pk_fma_f32 v[158:159], v[148:149], v[158:159], v[162:163]
	v_lshlrev_b32_e32 v162, 16, v155
	v_and_b32_e32 v163, 0xffff0000, v155
	v_pk_mul_f32 v[208:209], v[124:125], v[198:199] op_sel_hi:[1,0]
	v_pk_fma_f32 v[158:159], v[144:145], v[162:163], v[158:159]
	v_lshlrev_b32_e32 v162, 16, v160
	v_pk_mul_f32 v[158:159], v[208:209], v[158:159]
	v_and_b32_e32 v163, 0xffff0000, v160
	v_cvt_pk_bf16_f32 v155, v158, v159
	v_lshlrev_b32_e32 v158, 16, v164
	v_and_b32_e32 v159, 0xffff0000, v164
	v_pk_mul_f32 v[158:159], v[130:131], v[158:159]
	v_pk_mul_f32 v[214:215], v[118:119], v[198:199] op_sel_hi:[1,0]
	v_pk_fma_f32 v[158:159], v[134:135], v[162:163], v[158:159]
	v_lshlrev_b32_e32 v162, 16, v156
	v_and_b32_e32 v163, 0xffff0000, v156
	v_pk_fma_f32 v[158:159], v[138:139], v[162:163], v[158:159]
	v_and_b32_e32 v168, 0x1fff, v202
	v_pk_mul_f32 v[158:159], v[214:215], v[158:159]
	v_pk_mul_f32 v[216:217], v[150:151], v[216:217]
	v_cvt_pk_bf16_f32 v156, v158, v159
	v_lshlrev_b32_e32 v158, 16, v165
	v_and_b32_e32 v159, 0xffff0000, v165
	v_pk_mul_f32 v[158:159], v[132:133], v[158:159]
	v_lshlrev_b32_e32 v160, 16, v161
	v_and_b32_e32 v161, 0xffff0000, v161
	v_cmp_ne_u32_e32 vcc, 0, v168
	s_movk_i32 s14, 0x1fff
	v_pk_fma_f32 v[216:217], v[146:147], v[218:219], v[216:217]
	v_lshlrev_b32_e32 v218, 16, v154
	v_and_b32_e32 v219, 0xffff0000, v154
	v_pk_fma_f32 v[158:159], v[136:137], v[160:161], v[158:159]
	v_lshlrev_b32_e32 v160, 16, v157
	v_and_b32_e32 v161, 0xffff0000, v157
	s_and_b64 s[10:11], s[10:11], vcc
	v_cmp_ne_u32_e32 vcc, s14, v168
	v_pk_mul_f32 v[210:211], v[122:123], v[198:199] op_sel_hi:[1,0]
	v_pk_mul_f32 v[212:213], v[120:121], v[198:199] op_sel_hi:[1,0]
	v_pk_fma_f32 v[216:217], v[142:143], v[218:219], v[216:217]
	v_pk_fma_f32 v[158:159], v[140:141], v[160:161], v[158:159]
	v_lshlrev_b64 v[204:205], 10, v[202:203]
	s_and_b64 s[12:13], s[12:13], vcc
	v_pk_mul_f32 v[216:217], v[210:211], v[216:217]
	v_pk_mul_f32 v[158:159], v[212:213], v[158:159]
	v_cvt_pk_bf16_f32 v154, v216, v217
	v_cvt_pk_bf16_f32 v157, v158, v159
	s_nor_b64 s[10:11], s[10:11], s[12:13]
	v_lshl_add_u64 v[204:205], v[204:205], 1, s[74:75]
	s_and_saveexec_b64 s[14:15], s[10:11]
	s_xor_b64 s[14:15], exec, s[14:15]
	s_cbranch_execz .LBB0_298
	v_lshl_add_u64 v[158:159], v[206:207], 1, v[204:205]
	global_store_dwordx4 v[158:159], v[154:157], off

; __device__ __forceinline__ unsigned cvt_pk_bf16(float lo, float hi) { f32x2_t v = {lo, hi}; bf16x2_t b = __builtin_convertvector(v, bf16x2_t); return __builtin_bit_cast(unsigned, b); }
;     __device__ __forceinline__ void operator()(const f32x4 (&acc)[2][2][4][2], const Unit& u, int wr, int wc, int fr, int fq) const {
;     ...
;                     for (int m = 0; m < 4; ++m) { const int row = row0 + ai * HALF + m * 16, sq = row & 8191, lr = row & 255; const float r = rr[ai][m];
;                         const bool up_in = lr != 0, dn_in = lr != 255, up_halo = !up_in && sq != 0, dn_halo = !dn_in && sq != 8191;
;                         const bf16_t* up = U + (size_t)row * 1024 + col; const u32x4 z0 = {0u, 0u, 0u, 0u};
;                         const u32x4 uc = *(const u32x4*)up, ul = up_in ? *(const u32x4*)(up - 1024) : z0, ur = dn_in ? *(const u32x4*)(up + 1024) : z0;
;                         const f32x4 b0 = acc[ai][bj][m][0] * r, b1 = acc[ai][bj][m][1] * r;
;                         u32x4 w;
;                         w.x = cvt_pk_bf16(b0[0] * (k0a[0] * bf_lo(ul.x) + k1a[0] * bf_lo(uc.x) + k2a[0] * bf_lo(ur.x)), b0[1] * (k0a[1] * bf_hi(ul.x) + k1a[1] * bf_hi(uc.x) + k2a[1] * bf_hi(ur.x)));
;                         w.y = cvt_pk_bf16(b0[2] * (k0a[2] * bf_lo(ul.y) + k1a[2] * bf_lo(uc.y) + k2a[2] * bf_lo(ur.y)), b0[3] * (k0a[3] * bf_hi(ul.y) + k1a[3] * bf_hi(uc.y) + k2a[3] * bf_hi(ur.y)));
;                         w.z = cvt_pk_bf16(b1[0] * (k0b[0] * bf_lo(ul.z) + k1b[0] * bf_lo(uc.z) + k2b[0] * bf_lo(ur.z)), b1[1] * (k0b[1] * bf_hi(ul.z) + k1b[1] * bf_hi(uc.z) + k2b[1] * bf_hi(ur.z)));
;                         w.w = cvt_pk_bf16(b1[2] * (k0b[2] * bf_lo(ul.w) + k1b[2] * bf_lo(uc.w) + k2b[2] * bf_lo(ur.w)), b1[3] * (k0b[3] * bf_hi(ul.w) + k1b[3] * bf_hi(uc.w) + k2b[3] * bf_hi(ur.w)));
;                         if (up_halo || dn_halo) { const size_t ho = (size_t)(2 * u.pm + (dn_halo ? 1 : 0)) * 1024 + col;
;                             u32x4 bw; bw.x = cvt_pk_bf16(b0[0], b0[1]); bw.y = cvt_pk_bf16(b0[2], b0[3]); bw.z = cvt_pk_bf16(b1[0], b1[1]); bw.w = cvt_pk_bf16(b1[2], b1[3]);
;                             *(u32x4*)(HZ + ho) = w; *(u32x4*)(HBg + ho) = bw; }
;                         else *(u32x4*)(Z + (size_t)row * 1024 + col) = w; }
.LBB0_300:
	s_or_b64 exec, exec, s[14:15]
	v_add_u32_e32 v208, 16, v202
	v_ashrrev_i32_e32 v209, 31, v208
	v_readlane_b32 s12, v252, 21
	v_lshlrev_b64 v[154:155], 11, v[208:209]
	v_readlane_b32 s13, v252, 22
	v_cmp_eq_u32_sdwa s[16:17], v208, v167 src0_sel:BYTE_0 src1_sel:DWORD
	v_mov_b32_e32 v162, 0
	v_lshl_add_u64 v[210:211], s[12:13], 0, v[154:155]
	v_lshl_add_u64 v[212:213], v[206:207], 1, v[210:211]
	ds_read_b128 v[158:161], v166 offset:1088
	v_mov_b32_e32 v154, 0
	v_cmp_ne_u32_sdwa s[12:13], v208, v167 src0_sel:BYTE_0 src1_sel:DWORD
	v_mov_b32_e32 v163, 0
	v_mov_b32_e32 v164, 0
	v_mov_b32_e32 v165, 0
	s_and_saveexec_b64 s[14:15], s[12:13]
	s_cbranch_execz .LBB0_302
	ds_read_b128 v[162:165], v166 offset:1024
.LBB0_302:
	s_or_b64 exec, exec, s[14:15]
	s_movk_i32 s14, 0xff
	v_cmp_eq_u32_sdwa s[18:19], v208, s14 src0_sel:BYTE_0 src1_sel:DWORD
	v_cmp_ne_u32_sdwa s[14:15], v208, s14 src0_sel:BYTE_0 src1_sel:DWORD
	v_mov_b32_e32 v155, 0
	v_mov_b32_e32 v156, 0
	v_mov_b32_e32 v157, 0
	s_and_saveexec_b64 s[20:21], s[14:15]
	s_cbranch_execz .LBB0_304
	ds_read_b128 v[154:157], v166 offset:1152
.LBB0_304:
	s_or_b64 exec, exec, s[20:21]
	v_lshlrev_b64 v[220:221], 10, v[208:209]
	v_and_b32_e32 v168, 0x1fff, v208
	s_waitcnt lgkmcnt(0)
	v_lshlrev_b32_e32 v208, 16, v162
	v_and_b32_e32 v209, 0xffff0000, v162
	v_lshlrev_b32_e32 v162, 16, v163
	v_and_b32_e32 v163, 0xffff0000, v163
	v_lshlrev_b32_e32 v222, 16, v158
	v_and_b32_e32 v223, 0xffff0000, v158
	v_pk_mul_f32 v[162:163], v[152:153], v[162:163]
	v_lshlrev_b32_e32 v158, 16, v159
	v_and_b32_e32 v159, 0xffff0000, v159
	v_pk_fma_f32 v[158:159], v[148:149], v[158:159], v[162:163]
	v_lshlrev_b32_e32 v162, 16, v155
	v_and_b32_e32 v163, 0xffff0000, v155
	v_pk_mul_f32 v[212:213], v[112:113], v[196:197] op_sel_hi:[1,0]
	v_pk_fma_f32 v[158:159], v[144:145], v[162:163], v[158:159]
	v_lshlrev_b32_e32 v162, 16, v160
	v_pk_mul_f32 v[158:159], v[212:213], v[158:159]
	v_and_b32_e32 v163, 0xffff0000, v160
	v_cvt_pk_bf16_f32 v155, v158, v159
	v_lshlrev_b32_e32 v158, 16, v164
	v_and_b32_e32 v159, 0xffff0000, v164
	v_pk_mul_f32 v[158:159], v[130:131], v[158:159]
	v_pk_mul_f32 v[218:219], v[102:103], v[196:197] op_sel_hi:[1,0]
	v_pk_fma_f32 v[158:159], v[134:135], v[162:163], v[158:159]
	v_lshlrev_b32_e32 v162, 16, v156
	v_and_b32_e32 v163, 0xffff0000, v156
	v_pk_fma_f32 v[158:159], v[138:139], v[162:163], v[158:159]
	v_pk_mul_f32 v[208:209], v[150:151], v[208:209]
	v_pk_mul_f32 v[158:159], v[218:219], v[158:159]
	v_lshlrev_b32_e32 v160, 16, v161
	v_cvt_pk_bf16_f32 v156, v158, v159
	v_lshlrev_b32_e32 v158, 16, v165
	v_and_b32_e32 v159, 0xffff0000, v165
	v_pk_mul_f32 v[158:159], v[132:133], v[158:159]
	v_and_b32_e32 v161, 0xffff0000, v161
	v_cmp_ne_u32_e32 vcc, 0, v168
	s_movk_i32 s20, 0x1fff
	v_pk_fma_f32 v[208:209], v[146:147], v[222:223], v[208:209]
	v_lshlrev_b32_e32 v222, 16, v154
	v_and_b32_e32 v223, 0xffff0000, v154
	v_pk_fma_f32 v[158:159], v[136:137], v[160:161], v[158:159]
	v_lshlrev_b32_e32 v160, 16, v157
	v_and_b32_e32 v161, 0xffff0000, v157
	s_and_b64 s[16:17], s[16:17], vcc
	v_cmp_ne_u32_e32 vcc, s20, v168
	v_pk_mul_f32 v[214:215], v[110:111], v[196:197] op_sel_hi:[1,0]
	v_pk_mul_f32 v[216:217], v[104:105], v[196:197] op_sel_hi:[1,0]
	v_pk_fma_f32 v[208:209], v[142:143], v[222:223], v[208:209]
	v_pk_fma_f32 v[158:159], v[140:141], v[160:161], v[158:159]
	s_and_b64 s[18:19], s[18:19], vcc
	v_pk_mul_f32 v[208:209], v[214:215], v[208:209]
	v_pk_mul_f32 v[158:159], v[216:217], v[158:159]
	v_cvt_pk_bf16_f32 v154, v208, v209
	v_cvt_pk_bf16_f32 v157, v158, v159
	s_nor_b64 s[16:17], s[16:17], s[18:19]
	v_lshl_add_u64 v[208:209], v[220:221], 1, s[74:75]
	s_and_saveexec_b64 s[20:21], s[16:17]
	s_xor_b64 s[20:21], exec, s[20:21]
	s_cbranch_execz .LBB0_306
	v_lshl_add_u64 v[158:159], v[206:207], 1, v[208:209]
	global_store_dwordx4 v[158:159], v[154:157], off

; __device__ __forceinline__ unsigned cvt_pk_bf16(float lo, float hi) { f32x2_t v = {lo, hi}; bf16x2_t b = __builtin_convertvector(v, bf16x2_t); return __builtin_bit_cast(unsigned, b); }
;     __device__ __forceinline__ void operator()(const f32x4 (&acc)[2][2][4][2], const Unit& u, int wr, int wc, int fr, int fq) const {
;     ...
;                     for (int m = 0; m < 4; ++m) { const int row = row0 + ai * HALF + m * 16, sq = row & 8191, lr = row & 255; const float r = rr[ai][m];
;                         const bool up_in = lr != 0, dn_in = lr != 255, up_halo = !up_in && sq != 0, dn_halo = !dn_in && sq != 8191;
;                         const bf16_t* up = U + (size_t)row * 1024 + col; const u32x4 z0 = {0u, 0u, 0u, 0u};
;                         const u32x4 uc = *(const u32x4*)up, ul = up_in ? *(const u32x4*)(up - 1024) : z0, ur = dn_in ? *(const u32x4*)(up + 1024) : z0;
;                         const f32x4 b0 = acc[ai][bj][m][0] * r, b1 = acc[ai][bj][m][1] * r;
;                         u32x4 w;
;                         w.x = cvt_pk_bf16(b0[0] * (k0a[0] * bf_lo(ul.x) + k1a[0] * bf_lo(uc.x) + k2a[0] * bf_lo(ur.x)), b0[1] * (k0a[1] * bf_hi(ul.x) + k1a[1] * bf_hi(uc.x) + k2a[1] * bf_hi(ur.x)));
;                         w.y = cvt_pk_bf16(b0[2] * (k0a[2] * bf_lo(ul.y) + k1a[2] * bf_lo(uc.y) + k2a[2] * bf_lo(ur.y)), b0[3] * (k0a[3] * bf_hi(ul.y) + k1a[3] * bf_hi(uc.y) + k2a[3] * bf_hi(ur.y)));
;                         w.z = cvt_pk_bf16(b1[0] * (k0b[0] * bf_lo(ul.z) + k1b[0] * bf_lo(uc.z) + k2b[0] * bf_lo(ur.z)), b1[1] * (k0b[1] * bf_hi(ul.z) + k1b[1] * bf_hi(uc.z) + k2b[1] * bf_hi(ur.z)));
;                         w.w = cvt_pk_bf16(b1[2] * (k0b[2] * bf_lo(ul.w) + k1b[2] * bf_lo(uc.w) + k2b[2] * bf_lo(ur.w)), b1[3] * (k0b[3] * bf_hi(ul.w) + k1b[3] * bf_hi(uc.w) + k2b[3] * bf_hi(ur.w)));
;                         if (up_halo || dn_halo) { const size_t ho = (size_t)(2 * u.pm + (dn_halo ? 1 : 0)) * 1024 + col;
;                             u32x4 bw; bw.x = cvt_pk_bf16(b0[0], b0[1]); bw.y = cvt_pk_bf16(b0[2], b0[3]); bw.z = cvt_pk_bf16(b1[0], b1[1]); bw.w = cvt_pk_bf16(b1[2], b1[3]);
;                             *(u32x4*)(HZ + ho) = w; *(u32x4*)(HBg + ho) = bw; }
;                         else *(u32x4*)(Z + (size_t)row * 1024 + col) = w; }
.LBB0_308:
	s_or_b64 exec, exec, s[20:21]
	v_add_u32_e32 v212, 32, v202
	v_ashrrev_i32_e32 v213, 31, v212
	v_readlane_b32 s18, v252, 21
	v_lshlrev_b64 v[154:155], 11, v[212:213]
	v_readlane_b32 s19, v252, 22
	v_cmp_eq_u32_sdwa s[22:23], v212, v167 src0_sel:BYTE_0 src1_sel:DWORD
	v_mov_b32_e32 v162, 0
	v_lshl_add_u64 v[214:215], s[18:19], 0, v[154:155]
	v_lshl_add_u64 v[216:217], v[206:207], 1, v[214:215]
	ds_read_b128 v[158:161], v166 offset:2112
	v_mov_b32_e32 v154, 0
	v_cmp_ne_u32_sdwa s[18:19], v212, v167 src0_sel:BYTE_0 src1_sel:DWORD
	v_mov_b32_e32 v163, 0
	v_mov_b32_e32 v164, 0
	v_mov_b32_e32 v165, 0
	s_and_saveexec_b64 s[20:21], s[18:19]
	s_cbranch_execz .LBB0_310
	ds_read_b128 v[162:165], v166 offset:2048
.LBB0_310:
	s_or_b64 exec, exec, s[20:21]
	s_movk_i32 s20, 0xff
	v_cmp_eq_u32_sdwa s[24:25], v212, s20 src0_sel:BYTE_0 src1_sel:DWORD
	v_cmp_ne_u32_sdwa s[20:21], v212, s20 src0_sel:BYTE_0 src1_sel:DWORD
	v_mov_b32_e32 v155, 0
	v_mov_b32_e32 v156, 0
	v_mov_b32_e32 v157, 0
	s_and_saveexec_b64 s[34:35], s[20:21]
	s_cbranch_execz .LBB0_312
	ds_read_b128 v[154:157], v166 offset:2176
.LBB0_312:
	s_or_b64 exec, exec, s[34:35]
	v_lshlrev_b64 v[224:225], 10, v[212:213]
	v_and_b32_e32 v168, 0x1fff, v212
	s_waitcnt lgkmcnt(0)
	v_lshlrev_b32_e32 v212, 16, v162
	v_and_b32_e32 v213, 0xffff0000, v162
	v_lshlrev_b32_e32 v162, 16, v163
	v_and_b32_e32 v163, 0xffff0000, v163
	v_lshlrev_b32_e32 v226, 16, v158
	v_and_b32_e32 v227, 0xffff0000, v158
	v_pk_mul_f32 v[162:163], v[152:153], v[162:163]
	v_lshlrev_b32_e32 v158, 16, v159
	v_and_b32_e32 v159, 0xffff0000, v159
	v_pk_fma_f32 v[158:159], v[148:149], v[158:159], v[162:163]
	v_lshlrev_b32_e32 v162, 16, v155
	v_and_b32_e32 v163, 0xffff0000, v155
	v_pk_mul_f32 v[216:217], v[96:97], v[192:193] op_sel_hi:[1,0]
	v_pk_fma_f32 v[158:159], v[144:145], v[162:163], v[158:159]
	v_lshlrev_b32_e32 v162, 16, v160
	v_pk_mul_f32 v[158:159], v[216:217], v[158:159]
	v_and_b32_e32 v163, 0xffff0000, v160
	v_cvt_pk_bf16_f32 v155, v158, v159
	v_lshlrev_b32_e32 v158, 16, v164
	v_and_b32_e32 v159, 0xffff0000, v164
	v_pk_mul_f32 v[158:159], v[130:131], v[158:159]
	v_pk_mul_f32 v[222:223], v[86:87], v[192:193] op_sel_hi:[1,0]
	v_pk_fma_f32 v[158:159], v[134:135], v[162:163], v[158:159]
	v_lshlrev_b32_e32 v162, 16, v156
	v_and_b32_e32 v163, 0xffff0000, v156
	v_pk_fma_f32 v[158:159], v[138:139], v[162:163], v[158:159]
	v_pk_mul_f32 v[212:213], v[150:151], v[212:213]
	v_pk_mul_f32 v[158:159], v[222:223], v[158:159]
	v_lshlrev_b32_e32 v160, 16, v161
	v_cvt_pk_bf16_f32 v156, v158, v159
	v_lshlrev_b32_e32 v158, 16, v165
	v_and_b32_e32 v159, 0xffff0000, v165
	v_pk_mul_f32 v[158:159], v[132:133], v[158:159]
	v_and_b32_e32 v161, 0xffff0000, v161
	v_cmp_ne_u32_e32 vcc, 0, v168
	s_movk_i32 s34, 0x1fff
	v_pk_fma_f32 v[212:213], v[146:147], v[226:227], v[212:213]
	v_lshlrev_b32_e32 v226, 16, v154
	v_and_b32_e32 v227, 0xffff0000, v154
	v_pk_fma_f32 v[158:159], v[136:137], v[160:161], v[158:159]
	v_lshlrev_b32_e32 v160, 16, v157
	v_and_b32_e32 v161, 0xffff0000, v157
	s_and_b64 s[22:23], s[22:23], vcc
	v_cmp_ne_u32_e32 vcc, s34, v168
	v_pk_mul_f32 v[218:219], v[94:95], v[192:193] op_sel_hi:[1,0]
	v_pk_mul_f32 v[220:221], v[88:89], v[192:193] op_sel_hi:[1,0]
	v_pk_fma_f32 v[212:213], v[142:143], v[226:227], v[212:213]
	v_pk_fma_f32 v[158:159], v[140:141], v[160:161], v[158:159]
	s_and_b64 s[24:25], s[24:25], vcc
	v_pk_mul_f32 v[212:213], v[218:219], v[212:213]
	v_pk_mul_f32 v[158:159], v[220:221], v[158:159]
	v_cvt_pk_bf16_f32 v154, v212, v213
	v_cvt_pk_bf16_f32 v157, v158, v159
	s_nor_b64 s[22:23], s[22:23], s[24:25]
	v_lshl_add_u64 v[212:213], v[224:225], 1, s[74:75]
	s_and_saveexec_b64 s[34:35], s[22:23]
	s_xor_b64 s[34:35], exec, s[34:35]
	s_cbranch_execz .LBB0_314
	v_lshl_add_u64 v[158:159], v[206:207], 1, v[212:213]
	global_store_dwordx4 v[158:159], v[154:157], off

; __device__ __forceinline__ unsigned cvt_pk_bf16(float lo, float hi) { f32x2_t v = {lo, hi}; bf16x2_t b = __builtin_convertvector(v, bf16x2_t); return __builtin_bit_cast(unsigned, b); }
;     __device__ __forceinline__ void operator()(const f32x4 (&acc)[2][2][4][2], const Unit& u, int wr, int wc, int fr, int fq) const {
;     ...
;                     for (int m = 0; m < 4; ++m) { const int row = row0 + ai * HALF + m * 16, sq = row & 8191, lr = row & 255; const float r = rr[ai][m];
;                         const bool up_in = lr != 0, dn_in = lr != 255, up_halo = !up_in && sq != 0, dn_halo = !dn_in && sq != 8191;
;                         const bf16_t* up = U + (size_t)row * 1024 + col; const u32x4 z0 = {0u, 0u, 0u, 0u};
;                         const u32x4 uc = *(const u32x4*)up, ul = up_in ? *(const u32x4*)(up - 1024) : z0, ur = dn_in ? *(const u32x4*)(up + 1024) : z0;
;                         const f32x4 b0 = acc[ai][bj][m][0] * r, b1 = acc[ai][bj][m][1] * r;
;                         u32x4 w;
;                         w.x = cvt_pk_bf16(b0[0] * (k0a[0] * bf_lo(ul.x) + k1a[0] * bf_lo(uc.x) + k2a[0] * bf_lo(ur.x)), b0[1] * (k0a[1] * bf_hi(ul.x) + k1a[1] * bf_hi(uc.x) + k2a[1] * bf_hi(ur.x)));
;                         w.y = cvt_pk_bf16(b0[2] * (k0a[2] * bf_lo(ul.y) + k1a[2] * bf_lo(uc.y) + k2a[2] * bf_lo(ur.y)), b0[3] * (k0a[3] * bf_hi(ul.y) + k1a[3] * bf_hi(uc.y) + k2a[3] * bf_hi(ur.y)));
;                         w.z = cvt_pk_bf16(b1[0] * (k0b[0] * bf_lo(ul.z) + k1b[0] * bf_lo(uc.z) + k2b[0] * bf_lo(ur.z)), b1[1] * (k0b[1] * bf_hi(ul.z) + k1b[1] * bf_hi(uc.z) + k2b[1] * bf_hi(ur.z)));
;                         w.w = cvt_pk_bf16(b1[2] * (k0b[2] * bf_lo(ul.w) + k1b[2] * bf_lo(uc.w) + k2b[2] * bf_lo(ur.w)), b1[3] * (k0b[3] * bf_hi(ul.w) + k1b[3] * bf_hi(uc.w) + k2b[3] * bf_hi(ur.w)));
;                         if (up_halo || dn_halo) { const size_t ho = (size_t)(2 * u.pm + (dn_halo ? 1 : 0)) * 1024 + col;
;                             u32x4 bw; bw.x = cvt_pk_bf16(b0[0], b0[1]); bw.y = cvt_pk_bf16(b0[2], b0[3]); bw.z = cvt_pk_bf16(b1[0], b1[1]); bw.w = cvt_pk_bf16(b1[2], b1[3]);
;                             *(u32x4*)(HZ + ho) = w; *(u32x4*)(HBg + ho) = bw; }
;                         else *(u32x4*)(Z + (size_t)row * 1024 + col) = w; }
.LBB0_316:
	s_or_b64 exec, exec, s[34:35]
	v_add_u32_e32 v216, 48, v202
	v_ashrrev_i32_e32 v217, 31, v216
	v_readlane_b32 s24, v252, 21
	v_lshlrev_b64 v[154:155], 11, v[216:217]
	v_readlane_b32 s25, v252, 22
	v_cmp_eq_u32_sdwa s[34:35], v216, v167 src0_sel:BYTE_0 src1_sel:DWORD
	v_mov_b32_e32 v162, 0
	v_lshl_add_u64 v[218:219], s[24:25], 0, v[154:155]
	v_lshl_add_u64 v[220:221], v[206:207], 1, v[218:219]
	ds_read_b128 v[158:161], v166 offset:3136
	v_mov_b32_e32 v154, 0
	v_cmp_ne_u32_sdwa s[24:25], v216, v167 src0_sel:BYTE_0 src1_sel:DWORD
	v_mov_b32_e32 v163, 0
	v_mov_b32_e32 v164, 0
	v_mov_b32_e32 v165, 0
	s_and_saveexec_b64 s[42:43], s[24:25]
	s_cbranch_execz .LBB0_318
	ds_read_b128 v[162:165], v166 offset:3072
.LBB0_318:
	s_or_b64 exec, exec, s[42:43]
	s_movk_i32 s38, 0xff
	v_cmp_eq_u32_sdwa s[42:43], v216, s38 src0_sel:BYTE_0 src1_sel:DWORD
	v_cmp_ne_u32_sdwa s[82:83], v216, s38 src0_sel:BYTE_0 src1_sel:DWORD
	v_mov_b32_e32 v155, 0
	v_mov_b32_e32 v156, 0
	v_mov_b32_e32 v157, 0
	s_and_saveexec_b64 s[44:45], s[82:83]
	s_cbranch_execz .LBB0_320
	ds_read_b128 v[154:157], v166 offset:3200
.LBB0_320:
	s_or_b64 exec, exec, s[44:45]
	v_lshlrev_b64 v[228:229], 10, v[216:217]
	v_and_b32_e32 v168, 0x1fff, v216
	s_waitcnt lgkmcnt(0)
	v_lshlrev_b32_e32 v216, 16, v162
	v_and_b32_e32 v217, 0xffff0000, v162
	v_lshlrev_b32_e32 v162, 16, v163
	v_and_b32_e32 v163, 0xffff0000, v163
	v_lshlrev_b32_e32 v230, 16, v158
	v_and_b32_e32 v231, 0xffff0000, v158
	v_pk_mul_f32 v[162:163], v[152:153], v[162:163]
	v_lshlrev_b32_e32 v158, 16, v159
	v_and_b32_e32 v159, 0xffff0000, v159
	v_pk_fma_f32 v[158:159], v[148:149], v[158:159], v[162:163]
	v_lshlrev_b32_e32 v162, 16, v155
	v_and_b32_e32 v163, 0xffff0000, v155
	v_pk_mul_f32 v[220:221], v[80:81], v[194:195] op_sel_hi:[1,0]
	v_pk_fma_f32 v[158:159], v[144:145], v[162:163], v[158:159]
	v_lshlrev_b32_e32 v162, 16, v160
	v_pk_mul_f32 v[158:159], v[220:221], v[158:159]
	v_and_b32_e32 v163, 0xffff0000, v160
	v_cvt_pk_bf16_f32 v155, v158, v159
	v_lshlrev_b32_e32 v158, 16, v164
	v_and_b32_e32 v159, 0xffff0000, v164
	v_pk_mul_f32 v[158:159], v[130:131], v[158:159]
	v_pk_mul_f32 v[226:227], v[70:71], v[194:195] op_sel_hi:[1,0]
	v_pk_fma_f32 v[158:159], v[134:135], v[162:163], v[158:159]
	v_lshlrev_b32_e32 v162, 16, v156
	v_and_b32_e32 v163, 0xffff0000, v156
	v_pk_fma_f32 v[158:159], v[138:139], v[162:163], v[158:159]
	v_pk_mul_f32 v[216:217], v[150:151], v[216:217]
	v_pk_mul_f32 v[158:159], v[226:227], v[158:159]
	v_lshlrev_b32_e32 v160, 16, v161
	v_cvt_pk_bf16_f32 v156, v158, v159
	v_lshlrev_b32_e32 v158, 16, v165
	v_and_b32_e32 v159, 0xffff0000, v165
	v_pk_mul_f32 v[158:159], v[132:133], v[158:159]
	v_and_b32_e32 v161, 0xffff0000, v161
	v_cmp_ne_u32_e32 vcc, 0, v168
	s_movk_i32 s38, 0x1fff
	v_pk_fma_f32 v[216:217], v[146:147], v[230:231], v[216:217]
	v_lshlrev_b32_e32 v230, 16, v154
	v_and_b32_e32 v231, 0xffff0000, v154
	v_pk_fma_f32 v[158:159], v[136:137], v[160:161], v[158:159]
	v_lshlrev_b32_e32 v160, 16, v157
	v_and_b32_e32 v161, 0xffff0000, v157
	s_and_b64 s[34:35], s[34:35], vcc
	v_cmp_ne_u32_e32 vcc, s38, v168
	v_pk_mul_f32 v[222:223], v[78:79], v[194:195] op_sel_hi:[1,0]
	v_pk_mul_f32 v[224:225], v[72:73], v[194:195] op_sel_hi:[1,0]
	v_pk_fma_f32 v[216:217], v[142:143], v[230:231], v[216:217]
	v_pk_fma_f32 v[158:159], v[140:141], v[160:161], v[158:159]
	s_and_b64 s[42:43], s[42:43], vcc
	v_pk_mul_f32 v[216:217], v[222:223], v[216:217]
	v_pk_mul_f32 v[158:159], v[224:225], v[158:159]
	v_cvt_pk_bf16_f32 v154, v216, v217
	v_cvt_pk_bf16_f32 v157, v158, v159
	s_nor_b64 s[34:35], s[34:35], s[42:43]
	v_lshl_add_u64 v[216:217], v[228:229], 1, s[74:75]
	s_and_saveexec_b64 s[44:45], s[34:35]
	s_xor_b64 s[44:45], exec, s[44:45]
	s_cbranch_execz .LBB0_322
	v_lshl_add_u64 v[158:159], v[206:207], 1, v[216:217]
	global_store_dwordx4 v[158:159], v[154:157], off

; __device__ __forceinline__ unsigned cvt_pk_bf16(float lo, float hi) { f32x2_t v = {lo, hi}; bf16x2_t b = __builtin_convertvector(v, bf16x2_t); return __builtin_bit_cast(unsigned, b); }
;     __device__ __forceinline__ void operator()(const f32x4 (&acc)[2][2][4][2], const Unit& u, int wr, int wc, int fr, int fq) const {
;     ...
;                     for (int m = 0; m < 4; ++m) { const int row = row0 + ai * HALF + m * 16, sq = row & 8191, lr = row & 255; const float r = rr[ai][m];
;                         const bool up_in = lr != 0, dn_in = lr != 255, up_halo = !up_in && sq != 0, dn_halo = !dn_in && sq != 8191;
;                         const bf16_t* up = U + (size_t)row * 1024 + col; const u32x4 z0 = {0u, 0u, 0u, 0u};
;                         const u32x4 uc = *(const u32x4*)up, ul = up_in ? *(const u32x4*)(up - 1024) : z0, ur = dn_in ? *(const u32x4*)(up + 1024) : z0;
;                         const f32x4 b0 = acc[ai][bj][m][0] * r, b1 = acc[ai][bj][m][1] * r;
;                         u32x4 w;
;                         w.x = cvt_pk_bf16(b0[0] * (k0a[0] * bf_lo(ul.x) + k1a[0] * bf_lo(uc.x) + k2a[0] * bf_lo(ur.x)), b0[1] * (k0a[1] * bf_hi(ul.x) + k1a[1] * bf_hi(uc.x) + k2a[1] * bf_hi(ur.x)));
;                         w.y = cvt_pk_bf16(b0[2] * (k0a[2] * bf_lo(ul.y) + k1a[2] * bf_lo(uc.y) + k2a[2] * bf_lo(ur.y)), b0[3] * (k0a[3] * bf_hi(ul.y) + k1a[3] * bf_hi(uc.y) + k2a[3] * bf_hi(ur.y)));
;                         w.z = cvt_pk_bf16(b1[0] * (k0b[0] * bf_lo(ul.z) + k1b[0] * bf_lo(uc.z) + k2b[0] * bf_lo(ur.z)), b1[1] * (k0b[1] * bf_hi(ul.z) + k1b[1] * bf_hi(uc.z) + k2b[1] * bf_hi(ur.z)));
;                         w.w = cvt_pk_bf16(b1[2] * (k0b[2] * bf_lo(ul.w) + k1b[2] * bf_lo(uc.w) + k2b[2] * bf_lo(ur.w)), b1[3] * (k0b[3] * bf_hi(ul.w) + k1b[3] * bf_hi(uc.w) + k2b[3] * bf_hi(ur.w)));
;                         if (up_halo || dn_halo) { const size_t ho = (size_t)(2 * u.pm + (dn_halo ? 1 : 0)) * 1024 + col;
;                             u32x4 bw; bw.x = cvt_pk_bf16(b0[0], b0[1]); bw.y = cvt_pk_bf16(b0[2], b0[3]); bw.z = cvt_pk_bf16(b1[0], b1[1]); bw.w = cvt_pk_bf16(b1[2], b1[3]);
;                             *(u32x4*)(HZ + ho) = w; *(u32x4*)(HBg + ho) = bw; }
;                         else *(u32x4*)(Z + (size_t)row * 1024 + col) = w; }
.LBB0_324:
	s_or_b64 exec, exec, s[44:45]
	v_add_u32_e32 v220, 0x80, v202
	v_ashrrev_i32_e32 v221, 31, v220
	v_readlane_b32 s38, v252, 21
	v_lshlrev_b64 v[154:155], 11, v[220:221]
	v_readlane_b32 s39, v252, 22
	v_cmp_eq_u32_sdwa s[42:43], v220, v167 src0_sel:BYTE_0 src1_sel:DWORD
	v_cmp_ne_u32_sdwa s[80:81], v220, v167 src0_sel:BYTE_0 src1_sel:DWORD
	v_lshl_add_u64 v[222:223], s[38:39], 0, v[154:155]
	v_lshl_add_u64 v[224:225], v[206:207], 1, v[222:223]
	ds_read_b128 v[158:161], v166 offset:4288
	v_mov_b32_e32 v154, 0
	v_mov_b32_e32 v162, 0
	v_mov_b32_e32 v163, 0
	v_mov_b32_e32 v164, 0
	v_mov_b32_e32 v165, 0
	s_and_saveexec_b64 s[44:45], s[80:81]
	s_cbranch_execz .LBB0_326
	ds_read_b128 v[162:165], v166 offset:4224
.LBB0_326:
	s_or_b64 exec, exec, s[44:45]
	s_movk_i32 s38, 0xff
	v_cmp_eq_u32_sdwa s[44:45], v220, s38 src0_sel:BYTE_0 src1_sel:DWORD
	v_cmp_ne_u32_sdwa s[72:73], v220, s38 src0_sel:BYTE_0 src1_sel:DWORD
	v_mov_b32_e32 v155, 0
	v_mov_b32_e32 v156, 0
	v_mov_b32_e32 v157, 0
	s_and_saveexec_b64 s[56:57], s[72:73]
	s_cbranch_execz .LBB0_328
	ds_read_b128 v[154:157], v166 offset:4352
.LBB0_328:
	s_or_b64 exec, exec, s[56:57]
	v_lshlrev_b64 v[232:233], 10, v[220:221]
	v_and_b32_e32 v168, 0x1fff, v220
	s_waitcnt lgkmcnt(0)
	v_lshlrev_b32_e32 v220, 16, v162
	v_and_b32_e32 v221, 0xffff0000, v162
	v_lshlrev_b32_e32 v162, 16, v163
	v_and_b32_e32 v163, 0xffff0000, v163
	v_lshlrev_b32_e32 v234, 16, v158
	v_and_b32_e32 v235, 0xffff0000, v158
	v_pk_mul_f32 v[162:163], v[152:153], v[162:163]
	v_lshlrev_b32_e32 v158, 16, v159
	v_and_b32_e32 v159, 0xffff0000, v159
	v_pk_fma_f32 v[158:159], v[148:149], v[158:159], v[162:163]
	v_lshlrev_b32_e32 v162, 16, v155
	v_and_b32_e32 v163, 0xffff0000, v155
	v_pk_mul_f32 v[224:225], v[64:65], v[190:191] op_sel_hi:[1,0]
	v_pk_fma_f32 v[158:159], v[144:145], v[162:163], v[158:159]
	v_lshlrev_b32_e32 v162, 16, v160
	v_pk_mul_f32 v[158:159], v[224:225], v[158:159]
	v_and_b32_e32 v163, 0xffff0000, v160
	v_cvt_pk_bf16_f32 v155, v158, v159
	v_lshlrev_b32_e32 v158, 16, v164
	v_and_b32_e32 v159, 0xffff0000, v164
	v_pk_mul_f32 v[158:159], v[130:131], v[158:159]
	v_pk_mul_f32 v[230:231], v[54:55], v[190:191] op_sel_hi:[1,0]
	v_pk_fma_f32 v[158:159], v[134:135], v[162:163], v[158:159]
	v_lshlrev_b32_e32 v162, 16, v156
	v_and_b32_e32 v163, 0xffff0000, v156
	v_pk_fma_f32 v[158:159], v[138:139], v[162:163], v[158:159]
	v_pk_mul_f32 v[220:221], v[150:151], v[220:221]
	v_pk_mul_f32 v[158:159], v[230:231], v[158:159]
	v_lshlrev_b32_e32 v160, 16, v161
	v_cvt_pk_bf16_f32 v156, v158, v159
	v_lshlrev_b32_e32 v158, 16, v165
	v_and_b32_e32 v159, 0xffff0000, v165
	v_pk_mul_f32 v[158:159], v[132:133], v[158:159]
	v_and_b32_e32 v161, 0xffff0000, v161
	v_cmp_ne_u32_e32 vcc, 0, v168
	s_movk_i32 s38, 0x1fff
	v_pk_fma_f32 v[220:221], v[146:147], v[234:235], v[220:221]
	v_lshlrev_b32_e32 v234, 16, v154
	v_and_b32_e32 v235, 0xffff0000, v154
	v_pk_fma_f32 v[158:159], v[136:137], v[160:161], v[158:159]
	v_lshlrev_b32_e32 v160, 16, v157
	v_and_b32_e32 v161, 0xffff0000, v157
	s_and_b64 s[56:57], s[42:43], vcc
	v_cmp_ne_u32_e32 vcc, s38, v168
	v_pk_mul_f32 v[226:227], v[62:63], v[190:191] op_sel_hi:[1,0]
	v_pk_mul_f32 v[228:229], v[56:57], v[190:191] op_sel_hi:[1,0]
	v_pk_fma_f32 v[220:221], v[142:143], v[234:235], v[220:221]
	v_pk_fma_f32 v[158:159], v[140:141], v[160:161], v[158:159]
	s_and_b64 s[42:43], s[44:45], vcc
	v_pk_mul_f32 v[220:221], v[226:227], v[220:221]
	v_pk_mul_f32 v[158:159], v[228:229], v[158:159]
	v_cvt_pk_bf16_f32 v154, v220, v221
	v_cvt_pk_bf16_f32 v157, v158, v159
	s_nor_b64 s[44:45], s[56:57], s[42:43]
	v_lshl_add_u64 v[220:221], v[232:233], 1, s[74:75]
	s_and_saveexec_b64 s[56:57], s[44:45]
	s_xor_b64 s[56:57], exec, s[56:57]
	s_cbranch_execz .LBB0_330
	v_lshl_add_u64 v[158:159], v[206:207], 1, v[220:221]
	global_store_dwordx4 v[158:159], v[154:157], off

; __device__ __forceinline__ unsigned cvt_pk_bf16(float lo, float hi) { f32x2_t v = {lo, hi}; bf16x2_t b = __builtin_convertvector(v, bf16x2_t); return __builtin_bit_cast(unsigned, b); }
;     __device__ __forceinline__ void operator()(const f32x4 (&acc)[2][2][4][2], const Unit& u, int wr, int wc, int fr, int fq) const {
;     ...
;                     for (int m = 0; m < 4; ++m) { const int row = row0 + ai * HALF + m * 16, sq = row & 8191, lr = row & 255; const float r = rr[ai][m];
;                         const bool up_in = lr != 0, dn_in = lr != 255, up_halo = !up_in && sq != 0, dn_halo = !dn_in && sq != 8191;
;                         const bf16_t* up = U + (size_t)row * 1024 + col; const u32x4 z0 = {0u, 0u, 0u, 0u};
;                         const u32x4 uc = *(const u32x4*)up, ul = up_in ? *(const u32x4*)(up - 1024) : z0, ur = dn_in ? *(const u32x4*)(up + 1024) : z0;
;                         const f32x4 b0 = acc[ai][bj][m][0] * r, b1 = acc[ai][bj][m][1] * r;
;                         u32x4 w;
;                         w.x = cvt_pk_bf16(b0[0] * (k0a[0] * bf_lo(ul.x) + k1a[0] * bf_lo(uc.x) + k2a[0] * bf_lo(ur.x)), b0[1] * (k0a[1] * bf_hi(ul.x) + k1a[1] * bf_hi(uc.x) + k2a[1] * bf_hi(ur.x)));
;                         w.y = cvt_pk_bf16(b0[2] * (k0a[2] * bf_lo(ul.y) + k1a[2] * bf_lo(uc.y) + k2a[2] * bf_lo(ur.y)), b0[3] * (k0a[3] * bf_hi(ul.y) + k1a[3] * bf_hi(uc.y) + k2a[3] * bf_hi(ur.y)));
;                         w.z = cvt_pk_bf16(b1[0] * (k0b[0] * bf_lo(ul.z) + k1b[0] * bf_lo(uc.z) + k2b[0] * bf_lo(ur.z)), b1[1] * (k0b[1] * bf_hi(ul.z) + k1b[1] * bf_hi(uc.z) + k2b[1] * bf_hi(ur.z)));
;                         w.w = cvt_pk_bf16(b1[2] * (k0b[2] * bf_lo(ul.w) + k1b[2] * bf_lo(uc.w) + k2b[2] * bf_lo(ur.w)), b1[3] * (k0b[3] * bf_hi(ul.w) + k1b[3] * bf_hi(uc.w) + k2b[3] * bf_hi(ur.w)));
;                         if (up_halo || dn_halo) { const size_t ho = (size_t)(2 * u.pm + (dn_halo ? 1 : 0)) * 1024 + col;
;                             u32x4 bw; bw.x = cvt_pk_bf16(b0[0], b0[1]); bw.y = cvt_pk_bf16(b0[2], b0[3]); bw.z = cvt_pk_bf16(b1[0], b1[1]); bw.w = cvt_pk_bf16(b1[2], b1[3]);
;                             *(u32x4*)(HZ + ho) = w; *(u32x4*)(HBg + ho) = bw; }
;                         else *(u32x4*)(Z + (size_t)row * 1024 + col) = w; }
.LBB0_332:
	s_or_b64 exec, exec, s[56:57]
	v_add_u32_e32 v224, 0x90, v202
	v_ashrrev_i32_e32 v225, 31, v224
	v_readlane_b32 s38, v252, 21
	v_lshlrev_b64 v[154:155], 11, v[224:225]
	v_readlane_b32 s39, v252, 22
	v_cmp_eq_u32_sdwa s[56:57], v224, v167 src0_sel:BYTE_0 src1_sel:DWORD
	v_cmp_ne_u32_sdwa s[42:43], v224, v167 src0_sel:BYTE_0 src1_sel:DWORD
	v_lshl_add_u64 v[226:227], s[38:39], 0, v[154:155]
	v_lshl_add_u64 v[228:229], v[206:207], 1, v[226:227]
	ds_read_b128 v[158:161], v166 offset:5312
	v_mov_b32_e32 v154, 0
	v_mov_b32_e32 v162, 0
	v_mov_b32_e32 v163, 0
	v_mov_b32_e32 v164, 0
	v_mov_b32_e32 v165, 0
	s_and_saveexec_b64 s[60:61], s[42:43]
	s_cbranch_execz .LBB0_334
	ds_read_b128 v[162:165], v166 offset:5248
.LBB0_334:
	s_or_b64 exec, exec, s[60:61]
	s_movk_i32 s38, 0xff
	v_cmp_eq_u32_sdwa s[60:61], v224, s38 src0_sel:BYTE_0 src1_sel:DWORD
	v_cmp_ne_u32_sdwa s[90:91], v224, s38 src0_sel:BYTE_0 src1_sel:DWORD
	v_mov_b32_e32 v155, 0
	v_mov_b32_e32 v156, 0
	v_mov_b32_e32 v157, 0
	s_and_saveexec_b64 s[78:79], s[90:91]
	s_cbranch_execz .LBB0_336
	ds_read_b128 v[154:157], v166 offset:5376
.LBB0_336:
	s_or_b64 exec, exec, s[78:79]
	v_lshlrev_b64 v[236:237], 10, v[224:225]
	v_and_b32_e32 v168, 0x1fff, v224
	s_waitcnt lgkmcnt(0)
	v_lshlrev_b32_e32 v224, 16, v162
	v_and_b32_e32 v225, 0xffff0000, v162
	v_lshlrev_b32_e32 v162, 16, v163
	v_and_b32_e32 v163, 0xffff0000, v163
	v_lshlrev_b32_e32 v238, 16, v158
	v_and_b32_e32 v239, 0xffff0000, v158
	v_pk_mul_f32 v[162:163], v[152:153], v[162:163]
	v_lshlrev_b32_e32 v158, 16, v159
	v_and_b32_e32 v159, 0xffff0000, v159
	v_pk_fma_f32 v[158:159], v[148:149], v[158:159], v[162:163]
	v_lshlrev_b32_e32 v162, 16, v155
	v_and_b32_e32 v163, 0xffff0000, v155
	v_pk_mul_f32 v[228:229], v[48:49], v[188:189] op_sel_hi:[1,0]
	v_pk_fma_f32 v[158:159], v[144:145], v[162:163], v[158:159]
	v_lshlrev_b32_e32 v162, 16, v160
	v_pk_mul_f32 v[158:159], v[228:229], v[158:159]
	v_and_b32_e32 v163, 0xffff0000, v160
	v_cvt_pk_bf16_f32 v155, v158, v159
	v_lshlrev_b32_e32 v158, 16, v164
	v_and_b32_e32 v159, 0xffff0000, v164
	v_pk_mul_f32 v[158:159], v[130:131], v[158:159]
	v_pk_mul_f32 v[234:235], v[38:39], v[188:189] op_sel_hi:[1,0]
	v_pk_fma_f32 v[158:159], v[134:135], v[162:163], v[158:159]
	v_lshlrev_b32_e32 v162, 16, v156
	v_and_b32_e32 v163, 0xffff0000, v156
	v_pk_fma_f32 v[158:159], v[138:139], v[162:163], v[158:159]
	v_pk_mul_f32 v[224:225], v[150:151], v[224:225]
	v_pk_mul_f32 v[158:159], v[234:235], v[158:159]
	v_lshlrev_b32_e32 v160, 16, v161
	v_cvt_pk_bf16_f32 v156, v158, v159
	v_lshlrev_b32_e32 v158, 16, v165
	v_and_b32_e32 v159, 0xffff0000, v165
	v_pk_mul_f32 v[158:159], v[132:133], v[158:159]
	v_and_b32_e32 v161, 0xffff0000, v161
	v_cmp_ne_u32_e32 vcc, 0, v168
	s_movk_i32 s38, 0x1fff
	v_pk_fma_f32 v[224:225], v[146:147], v[238:239], v[224:225]
	v_lshlrev_b32_e32 v238, 16, v154
	v_and_b32_e32 v239, 0xffff0000, v154
	v_pk_fma_f32 v[158:159], v[136:137], v[160:161], v[158:159]
	v_lshlrev_b32_e32 v160, 16, v157
	v_and_b32_e32 v161, 0xffff0000, v157
	s_and_b64 s[78:79], s[56:57], vcc
	v_cmp_ne_u32_e32 vcc, s38, v168
	v_pk_mul_f32 v[230:231], v[46:47], v[188:189] op_sel_hi:[1,0]
	v_pk_mul_f32 v[232:233], v[40:41], v[188:189] op_sel_hi:[1,0]
	v_pk_fma_f32 v[224:225], v[142:143], v[238:239], v[224:225]
	v_pk_fma_f32 v[158:159], v[140:141], v[160:161], v[158:159]
	s_and_b64 s[56:57], s[60:61], vcc
	v_pk_mul_f32 v[224:225], v[230:231], v[224:225]
	v_pk_mul_f32 v[158:159], v[232:233], v[158:159]
	v_cvt_pk_bf16_f32 v154, v224, v225
	v_cvt_pk_bf16_f32 v157, v158, v159
	s_nor_b64 s[92:93], s[78:79], s[56:57]
	v_lshl_add_u64 v[224:225], v[236:237], 1, s[74:75]
	s_and_saveexec_b64 s[60:61], s[92:93]
	s_xor_b64 s[60:61], exec, s[60:61]
	s_cbranch_execz .LBB0_338
	v_lshl_add_u64 v[158:159], v[206:207], 1, v[224:225]
	global_store_dwordx4 v[158:159], v[154:157], off

; __device__ __forceinline__ unsigned cvt_pk_bf16(float lo, float hi) { f32x2_t v = {lo, hi}; bf16x2_t b = __builtin_convertvector(v, bf16x2_t); return __builtin_bit_cast(unsigned, b); }
;     __device__ __forceinline__ void operator()(const f32x4 (&acc)[2][2][4][2], const Unit& u, int wr, int wc, int fr, int fq) const {
;     ...
;                     for (int m = 0; m < 4; ++m) { const int row = row0 + ai * HALF + m * 16, sq = row & 8191, lr = row & 255; const float r = rr[ai][m];
;                         const bool up_in = lr != 0, dn_in = lr != 255, up_halo = !up_in && sq != 0, dn_halo = !dn_in && sq != 8191;
;                         const bf16_t* up = U + (size_t)row * 1024 + col; const u32x4 z0 = {0u, 0u, 0u, 0u};
;                         const u32x4 uc = *(const u32x4*)up, ul = up_in ? *(const u32x4*)(up - 1024) : z0, ur = dn_in ? *(const u32x4*)(up + 1024) : z0;
;                         const f32x4 b0 = acc[ai][bj][m][0] * r, b1 = acc[ai][bj][m][1] * r;
;                         u32x4 w;
;                         w.x = cvt_pk_bf16(b0[0] * (k0a[0] * bf_lo(ul.x) + k1a[0] * bf_lo(uc.x) + k2a[0] * bf_lo(ur.x)), b0[1] * (k0a[1] * bf_hi(ul.x) + k1a[1] * bf_hi(uc.x) + k2a[1] * bf_hi(ur.x)));
;                         w.y = cvt_pk_bf16(b0[2] * (k0a[2] * bf_lo(ul.y) + k1a[2] * bf_lo(uc.y) + k2a[2] * bf_lo(ur.y)), b0[3] * (k0a[3] * bf_hi(ul.y) + k1a[3] * bf_hi(uc.y) + k2a[3] * bf_hi(ur.y)));
;                         w.z = cvt_pk_bf16(b1[0] * (k0b[0] * bf_lo(ul.z) + k1b[0] * bf_lo(uc.z) + k2b[0] * bf_lo(ur.z)), b1[1] * (k0b[1] * bf_hi(ul.z) + k1b[1] * bf_hi(uc.z) + k2b[1] * bf_hi(ur.z)));
;                         w.w = cvt_pk_bf16(b1[2] * (k0b[2] * bf_lo(ul.w) + k1b[2] * bf_lo(uc.w) + k2b[2] * bf_lo(ur.w)), b1[3] * (k0b[3] * bf_hi(ul.w) + k1b[3] * bf_hi(uc.w) + k2b[3] * bf_hi(ur.w)));
;                         if (up_halo || dn_halo) { const size_t ho = (size_t)(2 * u.pm + (dn_halo ? 1 : 0)) * 1024 + col;
;                             u32x4 bw; bw.x = cvt_pk_bf16(b0[0], b0[1]); bw.y = cvt_pk_bf16(b0[2], b0[3]); bw.z = cvt_pk_bf16(b1[0], b1[1]); bw.w = cvt_pk_bf16(b1[2], b1[3]);
;                             *(u32x4*)(HZ + ho) = w; *(u32x4*)(HBg + ho) = bw; }
;                         else *(u32x4*)(Z + (size_t)row * 1024 + col) = w; }
.LBB0_340:
	s_or_b64 exec, exec, s[60:61]
	v_add_u32_e32 v228, 0xa0, v202
	v_ashrrev_i32_e32 v229, 31, v228
	v_readlane_b32 s38, v252, 21
	v_lshlrev_b64 v[154:155], 11, v[228:229]
	v_readlane_b32 s39, v252, 22
	v_cmp_eq_u32_sdwa s[56:57], v228, v167 src0_sel:BYTE_0 src1_sel:DWORD
	v_cmp_ne_u32_sdwa s[94:95], v228, v167 src0_sel:BYTE_0 src1_sel:DWORD
	v_lshl_add_u64 v[230:231], s[38:39], 0, v[154:155]
	v_lshl_add_u64 v[232:233], v[206:207], 1, v[230:231]
	ds_read_b128 v[158:161], v166 offset:6336
	v_mov_b32_e32 v154, 0
	v_mov_b32_e32 v162, 0
	v_mov_b32_e32 v163, 0
	v_mov_b32_e32 v164, 0
	v_mov_b32_e32 v165, 0
	s_and_saveexec_b64 s[60:61], s[94:95]
	s_cbranch_execz .LBB0_342
	ds_read_b128 v[162:165], v166 offset:6272
.LBB0_342:
	s_or_b64 exec, exec, s[60:61]
	s_movk_i32 s38, 0xff
	v_cmp_eq_u32_sdwa s[60:61], v228, s38 src0_sel:BYTE_0 src1_sel:DWORD
	v_cmp_ne_u32_sdwa s[96:97], v228, s38 src0_sel:BYTE_0 src1_sel:DWORD
	v_mov_b32_e32 v155, 0
	v_mov_b32_e32 v156, 0
	v_mov_b32_e32 v157, 0
	s_and_saveexec_b64 s[78:79], s[96:97]
	s_cbranch_execz .LBB0_344
	ds_read_b128 v[154:157], v166 offset:6400
.LBB0_344:
	s_or_b64 exec, exec, s[78:79]
	v_lshlrev_b64 v[240:241], 10, v[228:229]
	v_and_b32_e32 v168, 0x1fff, v228
	s_waitcnt lgkmcnt(0)
	v_lshlrev_b32_e32 v228, 16, v162
	v_and_b32_e32 v229, 0xffff0000, v162
	v_lshlrev_b32_e32 v162, 16, v163
	v_and_b32_e32 v163, 0xffff0000, v163
	v_lshlrev_b32_e32 v246, 16, v158
	v_and_b32_e32 v247, 0xffff0000, v158
	v_pk_mul_f32 v[162:163], v[152:153], v[162:163]
	v_lshlrev_b32_e32 v158, 16, v159
	v_and_b32_e32 v159, 0xffff0000, v159
	v_pk_fma_f32 v[158:159], v[148:149], v[158:159], v[162:163]
	v_lshlrev_b32_e32 v162, 16, v155
	v_and_b32_e32 v163, 0xffff0000, v155
	v_pk_mul_f32 v[232:233], v[32:33], v[186:187] op_sel_hi:[1,0]
	v_pk_fma_f32 v[158:159], v[144:145], v[162:163], v[158:159]
	v_lshlrev_b32_e32 v162, 16, v160
	v_pk_mul_f32 v[158:159], v[232:233], v[158:159]
	v_and_b32_e32 v163, 0xffff0000, v160
	v_cvt_pk_bf16_f32 v155, v158, v159
	v_lshlrev_b32_e32 v158, 16, v164
	v_and_b32_e32 v159, 0xffff0000, v164
	v_pk_mul_f32 v[158:159], v[130:131], v[158:159]
	v_pk_mul_f32 v[238:239], v[22:23], v[186:187] op_sel_hi:[1,0]
	v_pk_fma_f32 v[158:159], v[134:135], v[162:163], v[158:159]
	v_lshlrev_b32_e32 v162, 16, v156
	v_and_b32_e32 v163, 0xffff0000, v156
	v_pk_fma_f32 v[158:159], v[138:139], v[162:163], v[158:159]
	v_pk_mul_f32 v[228:229], v[150:151], v[228:229]
	v_pk_mul_f32 v[158:159], v[238:239], v[158:159]
	v_lshlrev_b32_e32 v160, 16, v161
	v_cvt_pk_bf16_f32 v156, v158, v159
	v_lshlrev_b32_e32 v158, 16, v165
	v_and_b32_e32 v159, 0xffff0000, v165
	v_pk_mul_f32 v[158:159], v[132:133], v[158:159]
	v_and_b32_e32 v161, 0xffff0000, v161
	v_cmp_ne_u32_e32 vcc, 0, v168
	s_movk_i32 s38, 0x1fff
	v_pk_fma_f32 v[228:229], v[146:147], v[246:247], v[228:229]
	v_lshlrev_b32_e32 v246, 16, v154
	v_and_b32_e32 v247, 0xffff0000, v154
	v_pk_fma_f32 v[158:159], v[136:137], v[160:161], v[158:159]
	v_lshlrev_b32_e32 v160, 16, v157
	v_and_b32_e32 v161, 0xffff0000, v157
	s_and_b64 s[78:79], s[56:57], vcc
	v_cmp_ne_u32_e32 vcc, s38, v168
	v_pk_mul_f32 v[234:235], v[30:31], v[186:187] op_sel_hi:[1,0]
	v_pk_mul_f32 v[236:237], v[24:25], v[186:187] op_sel_hi:[1,0]
	v_pk_fma_f32 v[228:229], v[142:143], v[246:247], v[228:229]
	v_pk_fma_f32 v[158:159], v[140:141], v[160:161], v[158:159]
	s_and_b64 s[56:57], s[60:61], vcc
	v_pk_mul_f32 v[228:229], v[234:235], v[228:229]
	v_pk_mul_f32 v[158:159], v[236:237], v[158:159]
	v_cvt_pk_bf16_f32 v154, v228, v229
	v_cvt_pk_bf16_f32 v157, v158, v159
	s_nor_b64 s[88:89], s[78:79], s[56:57]
	v_lshl_add_u64 v[228:229], v[240:241], 1, s[74:75]
	s_and_saveexec_b64 s[60:61], s[88:89]
	s_xor_b64 s[60:61], exec, s[60:61]
	s_cbranch_execz .LBB0_346
	v_lshl_add_u64 v[158:159], v[206:207], 1, v[228:229]
	global_store_dwordx4 v[158:159], v[154:157], off

; __device__ __forceinline__ unsigned cvt_pk_bf16(float lo, float hi) { f32x2_t v = {lo, hi}; bf16x2_t b = __builtin_convertvector(v, bf16x2_t); return __builtin_bit_cast(unsigned, b); }
;     __device__ __forceinline__ void operator()(const f32x4 (&acc)[2][2][4][2], const Unit& u, int wr, int wc, int fr, int fq) const {
;     ...
;                     for (int m = 0; m < 4; ++m) { const int row = row0 + ai * HALF + m * 16, sq = row & 8191, lr = row & 255; const float r = rr[ai][m];
;                         const bool up_in = lr != 0, dn_in = lr != 255, up_halo = !up_in && sq != 0, dn_halo = !dn_in && sq != 8191;
;                         const bf16_t* up = U + (size_t)row * 1024 + col; const u32x4 z0 = {0u, 0u, 0u, 0u};
;                         const u32x4 uc = *(const u32x4*)up, ul = up_in ? *(const u32x4*)(up - 1024) : z0, ur = dn_in ? *(const u32x4*)(up + 1024) : z0;
;                         const f32x4 b0 = acc[ai][bj][m][0] * r, b1 = acc[ai][bj][m][1] * r;
;                         u32x4 w;
;                         w.x = cvt_pk_bf16(b0[0] * (k0a[0] * bf_lo(ul.x) + k1a[0] * bf_lo(uc.x) + k2a[0] * bf_lo(ur.x)), b0[1] * (k0a[1] * bf_hi(ul.x) + k1a[1] * bf_hi(uc.x) + k2a[1] * bf_hi(ur.x)));
;                         w.y = cvt_pk_bf16(b0[2] * (k0a[2] * bf_lo(ul.y) + k1a[2] * bf_lo(uc.y) + k2a[2] * bf_lo(ur.y)), b0[3] * (k0a[3] * bf_hi(ul.y) + k1a[3] * bf_hi(uc.y) + k2a[3] * bf_hi(ur.y)));
;                         w.z = cvt_pk_bf16(b1[0] * (k0b[0] * bf_lo(ul.z) + k1b[0] * bf_lo(uc.z) + k2b[0] * bf_lo(ur.z)), b1[1] * (k0b[1] * bf_hi(ul.z) + k1b[1] * bf_hi(uc.z) + k2b[1] * bf_hi(ur.z)));
;                         w.w = cvt_pk_bf16(b1[2] * (k0b[2] * bf_lo(ul.w) + k1b[2] * bf_lo(uc.w) + k2b[2] * bf_lo(ur.w)), b1[3] * (k0b[3] * bf_hi(ul.w) + k1b[3] * bf_hi(uc.w) + k2b[3] * bf_hi(ur.w)));
;                         if (up_halo || dn_halo) { const size_t ho = (size_t)(2 * u.pm + (dn_halo ? 1 : 0)) * 1024 + col;
;                             u32x4 bw; bw.x = cvt_pk_bf16(b0[0], b0[1]); bw.y = cvt_pk_bf16(b0[2], b0[3]); bw.z = cvt_pk_bf16(b1[0], b1[1]); bw.w = cvt_pk_bf16(b1[2], b1[3]);
;                             *(u32x4*)(HZ + ho) = w; *(u32x4*)(HBg + ho) = bw; }
;                         else *(u32x4*)(Z + (size_t)row * 1024 + col) = w; }
.LBB0_348:
	s_or_b64 exec, exec, s[60:61]
	v_add_u32_e32 v202, 0xb0, v202
	v_ashrrev_i32_e32 v203, 31, v202
	v_readlane_b32 s38, v252, 21
	v_lshlrev_b64 v[154:155], 11, v[202:203]
	v_readlane_b32 s39, v252, 22
	v_cmp_eq_u32_sdwa s[86:87], v202, v167 src0_sel:BYTE_0 src1_sel:DWORD
	v_cmp_ne_u32_sdwa s[60:61], v202, v167 src0_sel:BYTE_0 src1_sel:DWORD
	v_lshl_add_u64 v[232:233], s[38:39], 0, v[154:155]
	v_lshl_add_u64 v[234:235], v[206:207], 1, v[232:233]
	ds_read_b128 v[158:161], v166 offset:7360
	v_mov_b32_e32 v154, 0
	v_mov_b32_e32 v162, 0
	v_mov_b32_e32 v163, 0
	v_mov_b32_e32 v164, 0
	v_mov_b32_e32 v165, 0
	s_and_saveexec_b64 s[56:57], s[60:61]
	s_cbranch_execz .LBB0_350
	ds_read_b128 v[162:165], v166 offset:7296
.LBB0_350:
	s_or_b64 exec, exec, s[56:57]
	s_movk_i32 s38, 0xff
	v_cmp_eq_u32_sdwa s[78:79], v202, s38 src0_sel:BYTE_0 src1_sel:DWORD
	v_cmp_ne_u32_sdwa s[56:57], v202, s38 src0_sel:BYTE_0 src1_sel:DWORD
	v_mov_b32_e32 v155, 0
	v_mov_b32_e32 v156, 0
	v_mov_b32_e32 v157, 0
	s_and_saveexec_b64 vcc, s[56:57]
	s_cbranch_execz .LBB0_352
	ds_read_b128 v[154:157], v166 offset:7424
.LBB0_352:
	s_or_b64 exec, exec, vcc
	v_lshlrev_b64 v[168:169], 10, v[202:203]
	v_and_b32_e32 v170, 0x1fff, v202
	s_waitcnt lgkmcnt(0)
	v_lshlrev_b32_e32 v202, 16, v162
	v_and_b32_e32 v203, 0xffff0000, v162
	v_pk_mul_f32 v[150:151], v[150:151], v[202:203]
	v_lshlrev_b32_e32 v202, 16, v158
	v_and_b32_e32 v203, 0xffff0000, v158
	v_pk_fma_f32 v[146:147], v[146:147], v[202:203], v[150:151]
	v_lshlrev_b32_e32 v150, 16, v154
	v_and_b32_e32 v151, 0xffff0000, v154
	v_pk_fma_f32 v[142:143], v[142:143], v[150:151], v[146:147]
	v_lshlrev_b32_e32 v146, 16, v163
	v_and_b32_e32 v147, 0xffff0000, v163
	v_pk_mul_f32 v[146:147], v[152:153], v[146:147]
	v_lshlrev_b32_e32 v150, 16, v159
	v_and_b32_e32 v151, 0xffff0000, v159
	v_pk_fma_f32 v[146:147], v[148:149], v[150:151], v[146:147]
	v_lshlrev_b32_e32 v148, 16, v155
	v_and_b32_e32 v149, 0xffff0000, v155
	v_pk_mul_f32 v[234:235], v[16:17], v[184:185] op_sel_hi:[1,0]
	v_pk_mul_f32 v[236:237], v[14:15], v[184:185] op_sel_hi:[1,0]
	v_pk_fma_f32 v[144:145], v[144:145], v[148:149], v[146:147]
	v_pk_mul_f32 v[142:143], v[236:237], v[142:143]
	v_pk_mul_f32 v[144:145], v[234:235], v[144:145]
	v_cvt_pk_bf16_f32 v142, v142, v143
	v_cvt_pk_bf16_f32 v143, v144, v145
	v_lshlrev_b32_e32 v144, 16, v164
	v_and_b32_e32 v145, 0xffff0000, v164
	v_pk_mul_f32 v[130:131], v[130:131], v[144:145]
	v_lshlrev_b32_e32 v144, 16, v160
	v_and_b32_e32 v145, 0xffff0000, v160
	v_pk_fma_f32 v[130:131], v[134:135], v[144:145], v[130:131]
	v_lshlrev_b32_e32 v134, 16, v156
	v_and_b32_e32 v135, 0xffff0000, v156
	v_pk_mul_f32 v[240:241], v[6:7], v[184:185] op_sel_hi:[1,0]
	v_pk_fma_f32 v[130:131], v[138:139], v[134:135], v[130:131]
	v_cmp_ne_u32_e32 vcc, 0, v170
	v_pk_mul_f32 v[130:131], v[240:241], v[130:131]
	s_and_b64 s[38:39], s[86:87], vcc
	v_cvt_pk_bf16_f32 v144, v130, v131
	v_lshlrev_b32_e32 v130, 16, v165
	v_and_b32_e32 v131, 0xffff0000, v165
	v_pk_mul_f32 v[130:131], v[132:133], v[130:131]
	v_lshlrev_b32_e32 v132, 16, v161
	v_and_b32_e32 v133, 0xffff0000, v161
	s_movk_i32 s86, 0x1fff
	v_pk_fma_f32 v[130:131], v[136:137], v[132:133], v[130:131]
	v_lshlrev_b32_e32 v132, 16, v157
	v_and_b32_e32 v133, 0xffff0000, v157
	v_cmp_ne_u32_e32 vcc, s86, v170
	v_pk_mul_f32 v[238:239], v[8:9], v[184:185] op_sel_hi:[1,0]
	v_pk_fma_f32 v[130:131], v[140:141], v[132:133], v[130:131]
	s_and_b64 s[86:87], s[78:79], vcc
	v_pk_mul_f32 v[130:131], v[238:239], v[130:131]
	s_nor_b64 vcc, s[38:39], s[86:87]
	v_cvt_pk_bf16_f32 v145, v130, v131
	v_lshl_add_u64 v[202:203], v[168:169], 1, s[74:75]
	s_and_saveexec_b64 s[38:39], vcc
	s_xor_b64 s[78:79], exec, s[38:39]
	s_cbranch_execz .LBB0_354
	v_lshl_add_u64 v[130:131], v[206:207], 1, v[202:203]
	global_store_dwordx4 v[130:131], v[142:145], off

;     __device__ __forceinline__ void operator()(const f32x4 (&acc)[2][2][4][2], const Unit& u, int wr, int wc, int fr, int fq) const {
;     ...
;             for (int bj = 0; bj < 2; ++bj) {
;                 const int col = (u.pn - 8) * BM + bj * HALF + wc * 32 + 8 * fq;
;                 const f32x4 k0a = *(const f32x4*)(taps + col), k0b = *(const f32x4*)(taps + col + 4), k1a = *(const f32x4*)(taps + 1024 + col), k1b = *(const f32x4*)(taps + 1024 + col + 4),
;                             k2a = *(const f32x4*)(taps + 2048 + col), k2b = *(const f32x4*)(taps + 2048 + col + 4);
; #pragma unroll
;                 for (int ai = 0; ai < 2; ++ai)
; #pragma unroll
;                     for (int m = 0; m < 4; ++m) { const int row = row0 + ai * HALF + m * 16, sq = row & 8191, lr = row & 255; const float r = rr[ai][m];
;                         const bool up_in = lr != 0, dn_in = lr != 255, up_halo = !up_in && sq != 0, dn_halo = !dn_in && sq != 8191;
;                         const bf16_t* up = U + (size_t)row * 1024 + col; const u32x4 z0 = {0u, 0u, 0u, 0u};
;                         const u32x4 uc = *(const u32x4*)up, ul = up_in ? *(const u32x4*)(up - 1024) : z0, ur = dn_in ? *(const u32x4*)(up + 1024) : z0;
;                         const f32x4 b0 = acc[ai][bj][m][0] * r, b1 = acc[ai][bj][m][1] * r;
;                         u32x4 w;
;                         w.x = cvt_pk_bf16(b0[0] * (k0a[0] * bf_lo(ul.x) + k1a[0] * bf_lo(uc.x) + k2a[0] * bf_lo(ur.x)), b0[1] * (k0a[1] * bf_hi(ul.x) + k1a[1] * bf_hi(uc.x) + k2a[1] * bf_hi(ur.x)));
;                         w.y = cvt_pk_bf16(b0[2] * (k0a[2] * bf_lo(ul.y) + k1a[2] * bf_lo(uc.y) + k2a[2] * bf_lo(ur.y)), b0[3] * (k0a[3] * bf_hi(ul.y) + k1a[3] * bf_hi(uc.y) + k2a[3] * bf_hi(ur.y)));
;                         w.z = cvt_pk_bf16(b1[0] * (k0b[0] * bf_lo(ul.z) + k1b[0] * bf_lo(uc.z) + k2b[0] * bf_lo(ur.z)), b1[1] * (k0b[1] * bf_hi(ul.z) + k1b[1] * bf_hi(uc.z) + k2b[1] * bf_hi(ur.z)));
;                         w.w = cvt_pk_bf16(b1[2] * (k0b[2] * bf_lo(ul.w) + k1b[2] * bf_lo(uc.w) + k2b[2] * bf_lo(ur.w)), b1[3] * (k0b[3] * bf_hi(ul.w) + k1b[3] * bf_hi(uc.w) + k2b[3] * bf_hi(ur.w)));
;                         if (up_halo || dn_halo) { const size_t ho = (size_t)(2 * u.pm + (dn_halo ? 1 : 0)) * 1024 + col;
.LBB0_356:
	s_or_b64 exec, exec, s[78:79]
	s_nop 0
	v_or_b32_e32 v130, 0xfffff880, v250
	v_add_u32_e32 v206, s76, v130
	v_ashrrev_i32_e32 v207, 31, v206
	v_readlane_b32 s38, v255, 11
	v_lshlrev_b64 v[138:139], 2, v[206:207]
	v_readlane_b32 s39, v255, 12
	v_lshl_add_u64 v[234:235], v[206:207], 1, v[200:201]
	v_mov_b32_e32 v154, 0
	v_lshl_add_u64 v[134:135], s[38:39], 0, v[138:139]
	v_readlane_b32 s38, v255, 9
	v_readlane_b32 s39, v255, 10
	global_load_dwordx4 v[130:133], v[134:135], off offset:16
	global_load_dwordx4 v[150:153], v[134:135], off
	v_lshl_add_u64 v[140:141], s[38:39], 0, v[138:139]
	v_readlane_b32 s38, v255, 13
	v_readlane_b32 s39, v255, 14
	global_load_dwordx4 v[134:137], v[140:141], off offset:16
	global_load_dwordx4 v[146:149], v[140:141], off
	v_lshl_add_u64 v[142:143], s[38:39], 0, v[138:139]
	global_load_dwordx4 v[138:141], v[142:143], off offset:16
	s_nop 0
	global_load_dwordx4 v[142:145], v[142:143], off
	v_mov_b32_e32 v162, 0
	s_waitcnt lgkmcnt(0)
	v_and_b32_e32 v158, 63, v0
	v_and_b32_e32 v159, 15, v158
	v_lshrrev_b32_e32 v160, 4, v158
	v_lshrrev_b32_e32 v161, 2, v159
	v_lshl_add_u32 v161, v160, 2, v161
	v_sub_u32_e32 v161, v161, v159
	v_add_u32_e32 v161, -1, v161
	v_lshlrev_b32_e32 v161, 11, v161
	v_and_b32_e32 v159, 3, v159
	v_sub_u32_e32 v159, v159, v160
	v_lshl_add_u32 v162, v159, 4, v161
	v_ashrrev_i32_e32 v163, 31, v162
	v_lshl_add_u64 v[162:163], v[234:235], 0, v[162:163]
	v_lshrrev_b32_e32 v160, 3, v158
	v_min_u32_e32 v160, 1, v160
	v_mul_u32_u24_e32 v160, 0x1f000, v160
	v_mov_b32_e32 v161, 0
	v_mov_b32_e32 v159, 0
	s_mov_b32 m0, s101
	s_nop 0
	global_load_lds_dwordx4 v[162:163], off
	s_add_i32 m0, s101, 0x400
	v_mov_b32_e32 v158, 0x8000
	v_lshl_add_u64 v[164:165], v[162:163], 0, v[158:159]
	global_load_lds_dwordx4 v[164:165], off
	s_add_i32 m0, s101, 0x800
	v_mov_b32_e32 v158, 0x10000
	v_lshl_add_u64 v[164:165], v[162:163], 0, v[158:159]
	global_load_lds_dwordx4 v[164:165], off
	s_add_i32 m0, s101, 0xc00
	v_mov_b32_e32 v158, 0x18000
	v_lshl_add_u64 v[164:165], v[162:163], 0, v[158:159]
	global_load_lds_dwordx4 v[164:165], off
	s_add_i32 m0, s101, 0x1000
	v_mov_b32_e32 v158, 0x20000
	v_lshl_add_u64 v[164:165], v[162:163], 0, v[158:159]
	v_lshl_add_u64 v[164:165], v[164:165], 0, v[160:161]
	global_load_lds_dwordx4 v[164:165], off
	s_add_i32 m0, s101, 0x1400
	v_mov_b32_e32 v158, 0x47000
	v_lshl_add_u64 v[164:165], v[162:163], 0, v[158:159]
	global_load_lds_dwordx4 v[164:165], off
	s_add_i32 m0, s101, 0x1800
	v_mov_b32_e32 v158, 0x4f000
	v_lshl_add_u64 v[164:165], v[162:163], 0, v[158:159]
	global_load_lds_dwordx4 v[164:165], off
	s_add_i32 m0, s101, 0x1c00
	v_mov_b32_e32 v158, 0x57000
	v_lshl_add_u64 v[164:165], v[162:163], 0, v[158:159]
	global_load_lds_dwordx4 v[164:165], off
	s_add_i32 m0, s101, 0x2000
	v_mov_b32_e32 v158, 0x5f000
	v_lshl_add_u64 v[164:165], v[162:163], 0, v[158:159]
	global_load_lds_dwordx4 v[164:165], off
	s_waitcnt vmcnt(0)
	s_barrier
	v_mov_b32_e32 v162, 0
	v_mov_b32_e32 v163, 0
	v_mov_b32_e32 v164, 0
	v_mov_b32_e32 v165, 0
	ds_read_b128 v[158:161], v166 offset:64
	v_mov_b32_e32 v163, 0
	v_mov_b32_e32 v164, 0
	v_mov_b32_e32 v165, 0
	s_and_saveexec_b64 s[78:79], s[6:7]
	v_readlane_b32 s74, v254, 44
	v_readlane_b32 s75, v254, 45
	s_cbranch_execz .LBB0_358
	ds_read_b128 v[162:165], v166 offset:0
.LBB0_358:
	s_or_b64 exec, exec, s[78:79]
	v_mov_b32_e32 v155, 0
	v_mov_b32_e32 v156, 0
	v_mov_b32_e32 v157, 0
	s_and_saveexec_b64 s[6:7], s[8:9]
	s_cbranch_execz .LBB0_360
	ds_read_b128 v[154:157], v166 offset:128
.LBB0_360:
	s_or_b64 exec, exec, s[6:7]
	v_mov_b32_e32 v168, v198
	v_mov_b32_e32 v169, v198
	v_pk_mul_f32 v[234:235], v[128:129], v[168:169]
	v_pk_mul_f32 v[238:239], v[116:117], v[168:169]
	s_waitcnt lgkmcnt(0)
	v_lshlrev_b32_e32 v168, 16, v162
	v_and_b32_e32 v169, 0xffff0000, v162
	v_lshlrev_b32_e32 v162, 16, v163
	v_and_b32_e32 v163, 0xffff0000, v163
	v_lshlrev_b32_e32 v170, 16, v158
	v_and_b32_e32 v171, 0xffff0000, v158
	v_pk_mul_f32 v[162:163], v[152:153], v[162:163]
	v_lshlrev_b32_e32 v158, 16, v159
	v_and_b32_e32 v159, 0xffff0000, v159
	v_pk_fma_f32 v[158:159], v[148:149], v[158:159], v[162:163]
	v_lshlrev_b32_e32 v162, 16, v155
	v_and_b32_e32 v163, 0xffff0000, v155
	v_pk_fma_f32 v[158:159], v[144:145], v[162:163], v[158:159]
	v_lshlrev_b32_e32 v162, 16, v160
	v_pk_mul_f32 v[158:159], v[234:235], v[158:159]
	v_and_b32_e32 v163, 0xffff0000, v160
	v_cvt_pk_bf16_f32 v155, v158, v159
	v_lshlrev_b32_e32 v158, 16, v164
	v_and_b32_e32 v159, 0xffff0000, v164
	v_pk_mul_f32 v[158:159], v[130:131], v[158:159]
	v_mov_b32_e32 v199, v198
	v_pk_fma_f32 v[158:159], v[134:135], v[162:163], v[158:159]
	v_lshlrev_b32_e32 v162, 16, v156
	v_and_b32_e32 v163, 0xffff0000, v156
	v_pk_mul_f32 v[240:241], v[114:115], v[198:199]
	v_pk_fma_f32 v[158:159], v[138:139], v[162:163], v[158:159]
	v_pk_mul_f32 v[168:169], v[150:151], v[168:169]
	v_pk_mul_f32 v[158:159], v[240:241], v[158:159]
	v_lshlrev_b32_e32 v160, 16, v161
	v_cvt_pk_bf16_f32 v156, v158, v159
	v_lshlrev_b32_e32 v158, 16, v165
	v_and_b32_e32 v159, 0xffff0000, v165
	v_pk_mul_f32 v[158:159], v[132:133], v[158:159]
	v_and_b32_e32 v161, 0xffff0000, v161
	v_pk_fma_f32 v[168:169], v[146:147], v[170:171], v[168:169]
	v_lshlrev_b32_e32 v170, 16, v154
	v_and_b32_e32 v171, 0xffff0000, v154
	v_pk_fma_f32 v[158:159], v[136:137], v[160:161], v[158:159]
	v_lshlrev_b32_e32 v160, 16, v157
	v_and_b32_e32 v161, 0xffff0000, v157
	v_pk_mul_f32 v[236:237], v[126:127], v[198:199]
	v_pk_fma_f32 v[168:169], v[142:143], v[170:171], v[168:169]
	v_pk_fma_f32 v[158:159], v[140:141], v[160:161], v[158:159]
	v_pk_mul_f32 v[168:169], v[236:237], v[168:169]
	v_pk_mul_f32 v[158:159], v[238:239], v[158:159]
	v_cvt_pk_bf16_f32 v154, v168, v169
	v_cvt_pk_bf16_f32 v157, v158, v159
	s_and_saveexec_b64 s[6:7], s[10:11]
	s_xor_b64 s[6:7], exec, s[6:7]
	s_cbranch_execz .LBB0_362
	v_lshl_add_u64 v[158:159], v[206:207], 1, v[204:205]
	global_store_dwordx4 v[158:159], v[154:157], off

; __device__ __forceinline__ unsigned cvt_pk_bf16(float lo, float hi) { f32x2_t v = {lo, hi}; bf16x2_t b = __builtin_convertvector(v, bf16x2_t); return __builtin_bit_cast(unsigned, b); }
;     __device__ __forceinline__ void operator()(const f32x4 (&acc)[2][2][4][2], const Unit& u, int wr, int wc, int fr, int fq) const {
;     ...
;                     for (int m = 0; m < 4; ++m) { const int row = row0 + ai * HALF + m * 16, sq = row & 8191, lr = row & 255; const float r = rr[ai][m];
;                         const bool up_in = lr != 0, dn_in = lr != 255, up_halo = !up_in && sq != 0, dn_halo = !dn_in && sq != 8191;
;                         const bf16_t* up = U + (size_t)row * 1024 + col; const u32x4 z0 = {0u, 0u, 0u, 0u};
;                         const u32x4 uc = *(const u32x4*)up, ul = up_in ? *(const u32x4*)(up - 1024) : z0, ur = dn_in ? *(const u32x4*)(up + 1024) : z0;
;                         const f32x4 b0 = acc[ai][bj][m][0] * r, b1 = acc[ai][bj][m][1] * r;
;                         u32x4 w;
;                         w.x = cvt_pk_bf16(b0[0] * (k0a[0] * bf_lo(ul.x) + k1a[0] * bf_lo(uc.x) + k2a[0] * bf_lo(ur.x)), b0[1] * (k0a[1] * bf_hi(ul.x) + k1a[1] * bf_hi(uc.x) + k2a[1] * bf_hi(ur.x)));
;                         w.y = cvt_pk_bf16(b0[2] * (k0a[2] * bf_lo(ul.y) + k1a[2] * bf_lo(uc.y) + k2a[2] * bf_lo(ur.y)), b0[3] * (k0a[3] * bf_hi(ul.y) + k1a[3] * bf_hi(uc.y) + k2a[3] * bf_hi(ur.y)));
;                         w.z = cvt_pk_bf16(b1[0] * (k0b[0] * bf_lo(ul.z) + k1b[0] * bf_lo(uc.z) + k2b[0] * bf_lo(ur.z)), b1[1] * (k0b[1] * bf_hi(ul.z) + k1b[1] * bf_hi(uc.z) + k2b[1] * bf_hi(ur.z)));
;                         w.w = cvt_pk_bf16(b1[2] * (k0b[2] * bf_lo(ul.w) + k1b[2] * bf_lo(uc.w) + k2b[2] * bf_lo(ur.w)), b1[3] * (k0b[3] * bf_hi(ul.w) + k1b[3] * bf_hi(uc.w) + k2b[3] * bf_hi(ur.w)));
;                         if (up_halo || dn_halo) { const size_t ho = (size_t)(2 * u.pm + (dn_halo ? 1 : 0)) * 1024 + col;
;                             u32x4 bw; bw.x = cvt_pk_bf16(b0[0], b0[1]); bw.y = cvt_pk_bf16(b0[2], b0[3]); bw.z = cvt_pk_bf16(b1[0], b1[1]); bw.w = cvt_pk_bf16(b1[2], b1[3]);
;                             *(u32x4*)(HZ + ho) = w; *(u32x4*)(HBg + ho) = bw; }
;                         else *(u32x4*)(Z + (size_t)row * 1024 + col) = w; }
.LBB0_364:
	s_or_b64 exec, exec, s[6:7]
	v_lshl_add_u64 v[204:205], v[206:207], 1, v[210:211]
	ds_read_b128 v[158:161], v166 offset:1088
	v_mov_b32_e32 v154, 0
	v_mov_b32_e32 v162, 0
	v_mov_b32_e32 v163, 0
	v_mov_b32_e32 v164, 0
	v_mov_b32_e32 v165, 0
	s_and_saveexec_b64 s[6:7], s[12:13]
	s_cbranch_execz .LBB0_366
	ds_read_b128 v[162:165], v166 offset:1024
.LBB0_366:
	s_or_b64 exec, exec, s[6:7]
	v_mov_b32_e32 v155, 0
	v_mov_b32_e32 v156, 0
	v_mov_b32_e32 v157, 0
	s_and_saveexec_b64 s[6:7], s[14:15]
	s_cbranch_execz .LBB0_368
	ds_read_b128 v[154:157], v166 offset:1152
.LBB0_368:
	s_or_b64 exec, exec, s[6:7]
	v_mov_b32_e32 v168, v196
	v_mov_b32_e32 v169, v196
	v_pk_mul_f32 v[204:205], v[108:109], v[168:169]
	v_pk_mul_f32 v[234:235], v[100:101], v[168:169]
	s_waitcnt lgkmcnt(0)
	v_lshlrev_b32_e32 v168, 16, v162
	v_and_b32_e32 v169, 0xffff0000, v162
	v_lshlrev_b32_e32 v162, 16, v163
	v_and_b32_e32 v163, 0xffff0000, v163
	v_lshlrev_b32_e32 v170, 16, v158
	v_and_b32_e32 v171, 0xffff0000, v158
	v_pk_mul_f32 v[162:163], v[152:153], v[162:163]
	v_lshlrev_b32_e32 v158, 16, v159
	v_and_b32_e32 v159, 0xffff0000, v159
	v_pk_fma_f32 v[158:159], v[148:149], v[158:159], v[162:163]
	v_lshlrev_b32_e32 v162, 16, v155
	v_and_b32_e32 v163, 0xffff0000, v155
	v_pk_fma_f32 v[158:159], v[144:145], v[162:163], v[158:159]
	v_lshlrev_b32_e32 v162, 16, v160
	v_pk_mul_f32 v[158:159], v[204:205], v[158:159]
	v_and_b32_e32 v163, 0xffff0000, v160
	v_cvt_pk_bf16_f32 v155, v158, v159
	v_lshlrev_b32_e32 v158, 16, v164
	v_and_b32_e32 v159, 0xffff0000, v164
	v_pk_mul_f32 v[158:159], v[130:131], v[158:159]
	v_mov_b32_e32 v197, v196
	v_pk_fma_f32 v[158:159], v[134:135], v[162:163], v[158:159]
	v_lshlrev_b32_e32 v162, 16, v156
	v_and_b32_e32 v163, 0xffff0000, v156
	v_pk_mul_f32 v[236:237], v[98:99], v[196:197]
	v_pk_fma_f32 v[158:159], v[138:139], v[162:163], v[158:159]
	v_pk_mul_f32 v[168:169], v[150:151], v[168:169]
	v_pk_mul_f32 v[158:159], v[236:237], v[158:159]
	v_lshlrev_b32_e32 v160, 16, v161
	v_cvt_pk_bf16_f32 v156, v158, v159
	v_lshlrev_b32_e32 v158, 16, v165
	v_and_b32_e32 v159, 0xffff0000, v165
	v_pk_mul_f32 v[158:159], v[132:133], v[158:159]
	v_and_b32_e32 v161, 0xffff0000, v161
	v_pk_fma_f32 v[168:169], v[146:147], v[170:171], v[168:169]
	v_lshlrev_b32_e32 v170, 16, v154
	v_and_b32_e32 v171, 0xffff0000, v154
	v_pk_fma_f32 v[158:159], v[136:137], v[160:161], v[158:159]
	v_lshlrev_b32_e32 v160, 16, v157
	v_and_b32_e32 v161, 0xffff0000, v157
	v_pk_mul_f32 v[210:211], v[106:107], v[196:197]
	v_pk_fma_f32 v[168:169], v[142:143], v[170:171], v[168:169]
	v_pk_fma_f32 v[158:159], v[140:141], v[160:161], v[158:159]
	v_pk_mul_f32 v[168:169], v[210:211], v[168:169]
	v_pk_mul_f32 v[158:159], v[234:235], v[158:159]
	v_cvt_pk_bf16_f32 v154, v168, v169
	v_cvt_pk_bf16_f32 v157, v158, v159
	s_and_saveexec_b64 s[6:7], s[16:17]
	s_xor_b64 s[6:7], exec, s[6:7]
	s_cbranch_execz .LBB0_370
	v_lshl_add_u64 v[158:159], v[206:207], 1, v[208:209]
	global_store_dwordx4 v[158:159], v[154:157], off

; __device__ __forceinline__ unsigned cvt_pk_bf16(float lo, float hi) { f32x2_t v = {lo, hi}; bf16x2_t b = __builtin_convertvector(v, bf16x2_t); return __builtin_bit_cast(unsigned, b); }
;     __device__ __forceinline__ void operator()(const f32x4 (&acc)[2][2][4][2], const Unit& u, int wr, int wc, int fr, int fq) const {
;     ...
;                     for (int m = 0; m < 4; ++m) { const int row = row0 + ai * HALF + m * 16, sq = row & 8191, lr = row & 255; const float r = rr[ai][m];
;                         const bool up_in = lr != 0, dn_in = lr != 255, up_halo = !up_in && sq != 0, dn_halo = !dn_in && sq != 8191;
;                         const bf16_t* up = U + (size_t)row * 1024 + col; const u32x4 z0 = {0u, 0u, 0u, 0u};
;                         const u32x4 uc = *(const u32x4*)up, ul = up_in ? *(const u32x4*)(up - 1024) : z0, ur = dn_in ? *(const u32x4*)(up + 1024) : z0;
;                         const f32x4 b0 = acc[ai][bj][m][0] * r, b1 = acc[ai][bj][m][1] * r;
;                         u32x4 w;
;                         w.x = cvt_pk_bf16(b0[0] * (k0a[0] * bf_lo(ul.x) + k1a[0] * bf_lo(uc.x) + k2a[0] * bf_lo(ur.x)), b0[1] * (k0a[1] * bf_hi(ul.x) + k1a[1] * bf_hi(uc.x) + k2a[1] * bf_hi(ur.x)));
;                         w.y = cvt_pk_bf16(b0[2] * (k0a[2] * bf_lo(ul.y) + k1a[2] * bf_lo(uc.y) + k2a[2] * bf_lo(ur.y)), b0[3] * (k0a[3] * bf_hi(ul.y) + k1a[3] * bf_hi(uc.y) + k2a[3] * bf_hi(ur.y)));
;                         w.z = cvt_pk_bf16(b1[0] * (k0b[0] * bf_lo(ul.z) + k1b[0] * bf_lo(uc.z) + k2b[0] * bf_lo(ur.z)), b1[1] * (k0b[1] * bf_hi(ul.z) + k1b[1] * bf_hi(uc.z) + k2b[1] * bf_hi(ur.z)));
;                         w.w = cvt_pk_bf16(b1[2] * (k0b[2] * bf_lo(ul.w) + k1b[2] * bf_lo(uc.w) + k2b[2] * bf_lo(ur.w)), b1[3] * (k0b[3] * bf_hi(ul.w) + k1b[3] * bf_hi(uc.w) + k2b[3] * bf_hi(ur.w)));
;                         if (up_halo || dn_halo) { const size_t ho = (size_t)(2 * u.pm + (dn_halo ? 1 : 0)) * 1024 + col;
;                             u32x4 bw; bw.x = cvt_pk_bf16(b0[0], b0[1]); bw.y = cvt_pk_bf16(b0[2], b0[3]); bw.z = cvt_pk_bf16(b1[0], b1[1]); bw.w = cvt_pk_bf16(b1[2], b1[3]);
;                             *(u32x4*)(HZ + ho) = w; *(u32x4*)(HBg + ho) = bw; }
;                         else *(u32x4*)(Z + (size_t)row * 1024 + col) = w; }
.LBB0_372:
	s_or_b64 exec, exec, s[6:7]
	v_lshl_add_u64 v[204:205], v[206:207], 1, v[214:215]
	ds_read_b128 v[158:161], v166 offset:2112
	v_mov_b32_e32 v154, 0
	v_mov_b32_e32 v162, 0
	v_mov_b32_e32 v163, 0
	v_mov_b32_e32 v164, 0
	v_mov_b32_e32 v165, 0
	s_and_saveexec_b64 s[6:7], s[18:19]
	s_cbranch_execz .LBB0_374
	ds_read_b128 v[162:165], v166 offset:2048
.LBB0_374:
	s_or_b64 exec, exec, s[6:7]
	v_mov_b32_e32 v155, 0
	v_mov_b32_e32 v156, 0
	v_mov_b32_e32 v157, 0
	s_and_saveexec_b64 s[6:7], s[20:21]
	s_cbranch_execz .LBB0_376
	ds_read_b128 v[154:157], v166 offset:2176
.LBB0_376:
	s_or_b64 exec, exec, s[6:7]
	v_mov_b32_e32 v168, v192
	v_mov_b32_e32 v169, v192
	v_pk_mul_f32 v[204:205], v[92:93], v[168:169]
	v_pk_mul_f32 v[210:211], v[84:85], v[168:169]
	s_waitcnt lgkmcnt(0)
	v_lshlrev_b32_e32 v168, 16, v162
	v_and_b32_e32 v169, 0xffff0000, v162
	v_lshlrev_b32_e32 v162, 16, v163
	v_and_b32_e32 v163, 0xffff0000, v163
	v_lshlrev_b32_e32 v170, 16, v158
	v_and_b32_e32 v171, 0xffff0000, v158
	v_pk_mul_f32 v[162:163], v[152:153], v[162:163]
	v_lshlrev_b32_e32 v158, 16, v159
	v_and_b32_e32 v159, 0xffff0000, v159
	v_pk_fma_f32 v[158:159], v[148:149], v[158:159], v[162:163]
	v_lshlrev_b32_e32 v162, 16, v155
	v_and_b32_e32 v163, 0xffff0000, v155
	v_pk_fma_f32 v[158:159], v[144:145], v[162:163], v[158:159]
	v_lshlrev_b32_e32 v162, 16, v160
	v_pk_mul_f32 v[158:159], v[204:205], v[158:159]
	v_and_b32_e32 v163, 0xffff0000, v160
	v_cvt_pk_bf16_f32 v155, v158, v159
	v_lshlrev_b32_e32 v158, 16, v164
	v_and_b32_e32 v159, 0xffff0000, v164
	v_pk_mul_f32 v[158:159], v[130:131], v[158:159]
	v_mov_b32_e32 v193, v192
	v_pk_fma_f32 v[158:159], v[134:135], v[162:163], v[158:159]
	v_lshlrev_b32_e32 v162, 16, v156
	v_and_b32_e32 v163, 0xffff0000, v156
	v_pk_mul_f32 v[214:215], v[82:83], v[192:193]
	v_pk_fma_f32 v[158:159], v[138:139], v[162:163], v[158:159]
	v_pk_mul_f32 v[168:169], v[150:151], v[168:169]
	v_pk_mul_f32 v[158:159], v[214:215], v[158:159]
	v_lshlrev_b32_e32 v160, 16, v161
	v_cvt_pk_bf16_f32 v156, v158, v159
	v_lshlrev_b32_e32 v158, 16, v165
	v_and_b32_e32 v159, 0xffff0000, v165
	v_pk_mul_f32 v[158:159], v[132:133], v[158:159]
	v_and_b32_e32 v161, 0xffff0000, v161
	v_pk_fma_f32 v[168:169], v[146:147], v[170:171], v[168:169]
	v_lshlrev_b32_e32 v170, 16, v154
	v_and_b32_e32 v171, 0xffff0000, v154
	v_pk_fma_f32 v[158:159], v[136:137], v[160:161], v[158:159]
	v_lshlrev_b32_e32 v160, 16, v157
	v_and_b32_e32 v161, 0xffff0000, v157
	v_pk_mul_f32 v[208:209], v[90:91], v[192:193]
	v_pk_fma_f32 v[168:169], v[142:143], v[170:171], v[168:169]
	v_pk_fma_f32 v[158:159], v[140:141], v[160:161], v[158:159]
	v_pk_mul_f32 v[168:169], v[208:209], v[168:169]
	v_pk_mul_f32 v[158:159], v[210:211], v[158:159]
	v_cvt_pk_bf16_f32 v154, v168, v169
	v_cvt_pk_bf16_f32 v157, v158, v159
	s_and_saveexec_b64 s[6:7], s[22:23]
	s_xor_b64 s[6:7], exec, s[6:7]
	s_cbranch_execz .LBB0_378
	v_lshl_add_u64 v[158:159], v[206:207], 1, v[212:213]
	global_store_dwordx4 v[158:159], v[154:157], off

; __device__ __forceinline__ unsigned cvt_pk_bf16(float lo, float hi) { f32x2_t v = {lo, hi}; bf16x2_t b = __builtin_convertvector(v, bf16x2_t); return __builtin_bit_cast(unsigned, b); }
;     __device__ __forceinline__ void operator()(const f32x4 (&acc)[2][2][4][2], const Unit& u, int wr, int wc, int fr, int fq) const {
;     ...
;                     for (int m = 0; m < 4; ++m) { const int row = row0 + ai * HALF + m * 16, sq = row & 8191, lr = row & 255; const float r = rr[ai][m];
;                         const bool up_in = lr != 0, dn_in = lr != 255, up_halo = !up_in && sq != 0, dn_halo = !dn_in && sq != 8191;
;                         const bf16_t* up = U + (size_t)row * 1024 + col; const u32x4 z0 = {0u, 0u, 0u, 0u};
;                         const u32x4 uc = *(const u32x4*)up, ul = up_in ? *(const u32x4*)(up - 1024) : z0, ur = dn_in ? *(const u32x4*)(up + 1024) : z0;
;                         const f32x4 b0 = acc[ai][bj][m][0] * r, b1 = acc[ai][bj][m][1] * r;
;                         u32x4 w;
;                         w.x = cvt_pk_bf16(b0[0] * (k0a[0] * bf_lo(ul.x) + k1a[0] * bf_lo(uc.x) + k2a[0] * bf_lo(ur.x)), b0[1] * (k0a[1] * bf_hi(ul.x) + k1a[1] * bf_hi(uc.x) + k2a[1] * bf_hi(ur.x)));
;                         w.y = cvt_pk_bf16(b0[2] * (k0a[2] * bf_lo(ul.y) + k1a[2] * bf_lo(uc.y) + k2a[2] * bf_lo(ur.y)), b0[3] * (k0a[3] * bf_hi(ul.y) + k1a[3] * bf_hi(uc.y) + k2a[3] * bf_hi(ur.y)));
;                         w.z = cvt_pk_bf16(b1[0] * (k0b[0] * bf_lo(ul.z) + k1b[0] * bf_lo(uc.z) + k2b[0] * bf_lo(ur.z)), b1[1] * (k0b[1] * bf_hi(ul.z) + k1b[1] * bf_hi(uc.z) + k2b[1] * bf_hi(ur.z)));
;                         w.w = cvt_pk_bf16(b1[2] * (k0b[2] * bf_lo(ul.w) + k1b[2] * bf_lo(uc.w) + k2b[2] * bf_lo(ur.w)), b1[3] * (k0b[3] * bf_hi(ul.w) + k1b[3] * bf_hi(uc.w) + k2b[3] * bf_hi(ur.w)));
;                         if (up_halo || dn_halo) { const size_t ho = (size_t)(2 * u.pm + (dn_halo ? 1 : 0)) * 1024 + col;
;                             u32x4 bw; bw.x = cvt_pk_bf16(b0[0], b0[1]); bw.y = cvt_pk_bf16(b0[2], b0[3]); bw.z = cvt_pk_bf16(b1[0], b1[1]); bw.w = cvt_pk_bf16(b1[2], b1[3]);
;                             *(u32x4*)(HZ + ho) = w; *(u32x4*)(HBg + ho) = bw; }
;                         else *(u32x4*)(Z + (size_t)row * 1024 + col) = w; }
.LBB0_380:
	s_or_b64 exec, exec, s[6:7]
	v_lshl_add_u64 v[204:205], v[206:207], 1, v[218:219]
	ds_read_b128 v[158:161], v166 offset:3136
	v_mov_b32_e32 v154, 0
	v_mov_b32_e32 v162, 0
	v_mov_b32_e32 v163, 0
	v_mov_b32_e32 v164, 0
	v_mov_b32_e32 v165, 0
	s_and_saveexec_b64 s[6:7], s[24:25]
	s_cbranch_execz .LBB0_382
	ds_read_b128 v[162:165], v166 offset:3072
.LBB0_382:
	s_or_b64 exec, exec, s[6:7]
	v_mov_b32_e32 v155, 0
	v_mov_b32_e32 v156, 0
	v_mov_b32_e32 v157, 0
	s_and_saveexec_b64 s[6:7], s[82:83]
	s_cbranch_execz .LBB0_384
	ds_read_b128 v[154:157], v166 offset:3200
.LBB0_384:
	s_or_b64 exec, exec, s[6:7]
	v_mov_b32_e32 v168, v194
	v_mov_b32_e32 v169, v194
	v_pk_mul_f32 v[204:205], v[76:77], v[168:169]
	v_pk_mul_f32 v[210:211], v[68:69], v[168:169]
	s_waitcnt lgkmcnt(0)
	v_lshlrev_b32_e32 v168, 16, v162
	v_and_b32_e32 v169, 0xffff0000, v162
	v_lshlrev_b32_e32 v162, 16, v163
	v_and_b32_e32 v163, 0xffff0000, v163
	v_lshlrev_b32_e32 v170, 16, v158
	v_and_b32_e32 v171, 0xffff0000, v158
	v_pk_mul_f32 v[162:163], v[152:153], v[162:163]
	v_lshlrev_b32_e32 v158, 16, v159
	v_and_b32_e32 v159, 0xffff0000, v159
	v_pk_fma_f32 v[158:159], v[148:149], v[158:159], v[162:163]
	v_lshlrev_b32_e32 v162, 16, v155
	v_and_b32_e32 v163, 0xffff0000, v155
	v_pk_fma_f32 v[158:159], v[144:145], v[162:163], v[158:159]
	v_lshlrev_b32_e32 v162, 16, v160
	v_pk_mul_f32 v[158:159], v[204:205], v[158:159]
	v_and_b32_e32 v163, 0xffff0000, v160
	v_cvt_pk_bf16_f32 v155, v158, v159
	v_lshlrev_b32_e32 v158, 16, v164
	v_and_b32_e32 v159, 0xffff0000, v164
	v_pk_mul_f32 v[158:159], v[130:131], v[158:159]
	v_mov_b32_e32 v195, v194
	v_pk_fma_f32 v[158:159], v[134:135], v[162:163], v[158:159]
	v_lshlrev_b32_e32 v162, 16, v156
	v_and_b32_e32 v163, 0xffff0000, v156
	v_pk_mul_f32 v[212:213], v[66:67], v[194:195]
	v_pk_fma_f32 v[158:159], v[138:139], v[162:163], v[158:159]
	v_pk_mul_f32 v[168:169], v[150:151], v[168:169]
	v_pk_mul_f32 v[158:159], v[212:213], v[158:159]
	v_lshlrev_b32_e32 v160, 16, v161
	v_cvt_pk_bf16_f32 v156, v158, v159
	v_lshlrev_b32_e32 v158, 16, v165
	v_and_b32_e32 v159, 0xffff0000, v165
	v_pk_mul_f32 v[158:159], v[132:133], v[158:159]
	v_and_b32_e32 v161, 0xffff0000, v161
	v_pk_fma_f32 v[168:169], v[146:147], v[170:171], v[168:169]
	v_lshlrev_b32_e32 v170, 16, v154
	v_and_b32_e32 v171, 0xffff0000, v154
	v_pk_fma_f32 v[158:159], v[136:137], v[160:161], v[158:159]
	v_lshlrev_b32_e32 v160, 16, v157
	v_and_b32_e32 v161, 0xffff0000, v157
	v_pk_mul_f32 v[208:209], v[74:75], v[194:195]
	v_pk_fma_f32 v[168:169], v[142:143], v[170:171], v[168:169]
	v_pk_fma_f32 v[158:159], v[140:141], v[160:161], v[158:159]
	v_pk_mul_f32 v[168:169], v[208:209], v[168:169]
	v_pk_mul_f32 v[158:159], v[210:211], v[158:159]
	v_cvt_pk_bf16_f32 v154, v168, v169
	v_cvt_pk_bf16_f32 v157, v158, v159
	s_and_saveexec_b64 s[6:7], s[34:35]
	s_xor_b64 s[6:7], exec, s[6:7]
	s_cbranch_execz .LBB0_386
	v_lshl_add_u64 v[158:159], v[206:207], 1, v[216:217]
	global_store_dwordx4 v[158:159], v[154:157], off

; __device__ __forceinline__ unsigned cvt_pk_bf16(float lo, float hi) { f32x2_t v = {lo, hi}; bf16x2_t b = __builtin_convertvector(v, bf16x2_t); return __builtin_bit_cast(unsigned, b); }
;     __device__ __forceinline__ void operator()(const f32x4 (&acc)[2][2][4][2], const Unit& u, int wr, int wc, int fr, int fq) const {
;     ...
;                     for (int m = 0; m < 4; ++m) { const int row = row0 + ai * HALF + m * 16, sq = row & 8191, lr = row & 255; const float r = rr[ai][m];
;                         const bool up_in = lr != 0, dn_in = lr != 255, up_halo = !up_in && sq != 0, dn_halo = !dn_in && sq != 8191;
;                         const bf16_t* up = U + (size_t)row * 1024 + col; const u32x4 z0 = {0u, 0u, 0u, 0u};
;                         const u32x4 uc = *(const u32x4*)up, ul = up_in ? *(const u32x4*)(up - 1024) : z0, ur = dn_in ? *(const u32x4*)(up + 1024) : z0;
;                         const f32x4 b0 = acc[ai][bj][m][0] * r, b1 = acc[ai][bj][m][1] * r;
;                         u32x4 w;
;                         w.x = cvt_pk_bf16(b0[0] * (k0a[0] * bf_lo(ul.x) + k1a[0] * bf_lo(uc.x) + k2a[0] * bf_lo(ur.x)), b0[1] * (k0a[1] * bf_hi(ul.x) + k1a[1] * bf_hi(uc.x) + k2a[1] * bf_hi(ur.x)));
;                         w.y = cvt_pk_bf16(b0[2] * (k0a[2] * bf_lo(ul.y) + k1a[2] * bf_lo(uc.y) + k2a[2] * bf_lo(ur.y)), b0[3] * (k0a[3] * bf_hi(ul.y) + k1a[3] * bf_hi(uc.y) + k2a[3] * bf_hi(ur.y)));
;                         w.z = cvt_pk_bf16(b1[0] * (k0b[0] * bf_lo(ul.z) + k1b[0] * bf_lo(uc.z) + k2b[0] * bf_lo(ur.z)), b1[1] * (k0b[1] * bf_hi(ul.z) + k1b[1] * bf_hi(uc.z) + k2b[1] * bf_hi(ur.z)));
;                         w.w = cvt_pk_bf16(b1[2] * (k0b[2] * bf_lo(ul.w) + k1b[2] * bf_lo(uc.w) + k2b[2] * bf_lo(ur.w)), b1[3] * (k0b[3] * bf_hi(ul.w) + k1b[3] * bf_hi(uc.w) + k2b[3] * bf_hi(ur.w)));
;                         if (up_halo || dn_halo) { const size_t ho = (size_t)(2 * u.pm + (dn_halo ? 1 : 0)) * 1024 + col;
;                             u32x4 bw; bw.x = cvt_pk_bf16(b0[0], b0[1]); bw.y = cvt_pk_bf16(b0[2], b0[3]); bw.z = cvt_pk_bf16(b1[0], b1[1]); bw.w = cvt_pk_bf16(b1[2], b1[3]);
;                             *(u32x4*)(HZ + ho) = w; *(u32x4*)(HBg + ho) = bw; }
;                         else *(u32x4*)(Z + (size_t)row * 1024 + col) = w; }
.LBB0_388:
	s_or_b64 exec, exec, s[6:7]
	v_lshl_add_u64 v[204:205], v[206:207], 1, v[222:223]
	ds_read_b128 v[158:161], v166 offset:4288
	v_mov_b32_e32 v154, 0
	v_mov_b32_e32 v162, 0
	v_mov_b32_e32 v163, 0
	v_mov_b32_e32 v164, 0
	v_mov_b32_e32 v165, 0
	s_and_saveexec_b64 s[6:7], s[80:81]
	s_cbranch_execz .LBB0_390
	ds_read_b128 v[162:165], v166 offset:4224
.LBB0_390:
	s_or_b64 exec, exec, s[6:7]
	v_mov_b32_e32 v155, 0
	v_mov_b32_e32 v156, 0
	v_mov_b32_e32 v157, 0
	s_and_saveexec_b64 s[6:7], s[72:73]
	s_cbranch_execz .LBB0_392
	ds_read_b128 v[154:157], v166 offset:4352
.LBB0_392:
	s_or_b64 exec, exec, s[6:7]
	v_mov_b32_e32 v168, v190
	v_mov_b32_e32 v169, v190
	v_pk_mul_f32 v[204:205], v[60:61], v[168:169]
	v_pk_mul_f32 v[210:211], v[52:53], v[168:169]
	s_waitcnt lgkmcnt(0)
	v_lshlrev_b32_e32 v168, 16, v162
	v_and_b32_e32 v169, 0xffff0000, v162
	v_lshlrev_b32_e32 v162, 16, v163
	v_and_b32_e32 v163, 0xffff0000, v163
	v_lshlrev_b32_e32 v170, 16, v158
	v_and_b32_e32 v171, 0xffff0000, v158
	v_pk_mul_f32 v[162:163], v[152:153], v[162:163]
	v_lshlrev_b32_e32 v158, 16, v159
	v_and_b32_e32 v159, 0xffff0000, v159
	v_pk_fma_f32 v[158:159], v[148:149], v[158:159], v[162:163]
	v_lshlrev_b32_e32 v162, 16, v155
	v_and_b32_e32 v163, 0xffff0000, v155
	v_pk_fma_f32 v[158:159], v[144:145], v[162:163], v[158:159]
	v_lshlrev_b32_e32 v162, 16, v160
	v_pk_mul_f32 v[158:159], v[204:205], v[158:159]
	v_and_b32_e32 v163, 0xffff0000, v160
	v_cvt_pk_bf16_f32 v155, v158, v159
	v_lshlrev_b32_e32 v158, 16, v164
	v_and_b32_e32 v159, 0xffff0000, v164
	v_pk_mul_f32 v[158:159], v[130:131], v[158:159]
	v_mov_b32_e32 v191, v190
	v_pk_fma_f32 v[158:159], v[134:135], v[162:163], v[158:159]
	v_lshlrev_b32_e32 v162, 16, v156
	v_and_b32_e32 v163, 0xffff0000, v156
	v_pk_mul_f32 v[212:213], v[50:51], v[190:191]
	v_pk_fma_f32 v[158:159], v[138:139], v[162:163], v[158:159]
	v_pk_mul_f32 v[168:169], v[150:151], v[168:169]
	v_pk_mul_f32 v[158:159], v[212:213], v[158:159]
	v_lshlrev_b32_e32 v160, 16, v161
	v_cvt_pk_bf16_f32 v156, v158, v159
	v_lshlrev_b32_e32 v158, 16, v165
	v_and_b32_e32 v159, 0xffff0000, v165
	v_pk_mul_f32 v[158:159], v[132:133], v[158:159]
	v_and_b32_e32 v161, 0xffff0000, v161
	v_pk_fma_f32 v[168:169], v[146:147], v[170:171], v[168:169]
	v_lshlrev_b32_e32 v170, 16, v154
	v_and_b32_e32 v171, 0xffff0000, v154
	v_pk_fma_f32 v[158:159], v[136:137], v[160:161], v[158:159]
	v_lshlrev_b32_e32 v160, 16, v157
	v_and_b32_e32 v161, 0xffff0000, v157
	v_pk_mul_f32 v[208:209], v[58:59], v[190:191]
	v_pk_fma_f32 v[168:169], v[142:143], v[170:171], v[168:169]
	v_pk_fma_f32 v[158:159], v[140:141], v[160:161], v[158:159]
	v_pk_mul_f32 v[168:169], v[208:209], v[168:169]
	v_pk_mul_f32 v[158:159], v[210:211], v[158:159]
	v_cvt_pk_bf16_f32 v154, v168, v169
	v_cvt_pk_bf16_f32 v157, v158, v159
	s_and_saveexec_b64 s[6:7], s[44:45]
	s_xor_b64 s[6:7], exec, s[6:7]
	s_cbranch_execz .LBB0_394
	v_lshl_add_u64 v[158:159], v[206:207], 1, v[220:221]
	global_store_dwordx4 v[158:159], v[154:157], off

; __device__ __forceinline__ unsigned cvt_pk_bf16(float lo, float hi) { f32x2_t v = {lo, hi}; bf16x2_t b = __builtin_convertvector(v, bf16x2_t); return __builtin_bit_cast(unsigned, b); }
;     __device__ __forceinline__ void operator()(const f32x4 (&acc)[2][2][4][2], const Unit& u, int wr, int wc, int fr, int fq) const {
;     ...
;                     for (int m = 0; m < 4; ++m) { const int row = row0 + ai * HALF + m * 16, sq = row & 8191, lr = row & 255; const float r = rr[ai][m];
;                         const bool up_in = lr != 0, dn_in = lr != 255, up_halo = !up_in && sq != 0, dn_halo = !dn_in && sq != 8191;
;                         const bf16_t* up = U + (size_t)row * 1024 + col; const u32x4 z0 = {0u, 0u, 0u, 0u};
;                         const u32x4 uc = *(const u32x4*)up, ul = up_in ? *(const u32x4*)(up - 1024) : z0, ur = dn_in ? *(const u32x4*)(up + 1024) : z0;
;                         const f32x4 b0 = acc[ai][bj][m][0] * r, b1 = acc[ai][bj][m][1] * r;
;                         u32x4 w;
;                         w.x = cvt_pk_bf16(b0[0] * (k0a[0] * bf_lo(ul.x) + k1a[0] * bf_lo(uc.x) + k2a[0] * bf_lo(ur.x)), b0[1] * (k0a[1] * bf_hi(ul.x) + k1a[1] * bf_hi(uc.x) + k2a[1] * bf_hi(ur.x)));
;                         w.y = cvt_pk_bf16(b0[2] * (k0a[2] * bf_lo(ul.y) + k1a[2] * bf_lo(uc.y) + k2a[2] * bf_lo(ur.y)), b0[3] * (k0a[3] * bf_hi(ul.y) + k1a[3] * bf_hi(uc.y) + k2a[3] * bf_hi(ur.y)));
;                         w.z = cvt_pk_bf16(b1[0] * (k0b[0] * bf_lo(ul.z) + k1b[0] * bf_lo(uc.z) + k2b[0] * bf_lo(ur.z)), b1[1] * (k0b[1] * bf_hi(ul.z) + k1b[1] * bf_hi(uc.z) + k2b[1] * bf_hi(ur.z)));
;                         w.w = cvt_pk_bf16(b1[2] * (k0b[2] * bf_lo(ul.w) + k1b[2] * bf_lo(uc.w) + k2b[2] * bf_lo(ur.w)), b1[3] * (k0b[3] * bf_hi(ul.w) + k1b[3] * bf_hi(uc.w) + k2b[3] * bf_hi(ur.w)));
;                         if (up_halo || dn_halo) { const size_t ho = (size_t)(2 * u.pm + (dn_halo ? 1 : 0)) * 1024 + col;
;                             u32x4 bw; bw.x = cvt_pk_bf16(b0[0], b0[1]); bw.y = cvt_pk_bf16(b0[2], b0[3]); bw.z = cvt_pk_bf16(b1[0], b1[1]); bw.w = cvt_pk_bf16(b1[2], b1[3]);
;                             *(u32x4*)(HZ + ho) = w; *(u32x4*)(HBg + ho) = bw; }
;                         else *(u32x4*)(Z + (size_t)row * 1024 + col) = w; }
.LBB0_396:
	s_or_b64 exec, exec, s[6:7]
	v_lshl_add_u64 v[204:205], v[206:207], 1, v[226:227]
	ds_read_b128 v[158:161], v166 offset:5312
	v_mov_b32_e32 v154, 0
	v_mov_b32_e32 v162, 0
	v_mov_b32_e32 v163, 0
	v_mov_b32_e32 v164, 0
	v_mov_b32_e32 v165, 0
	s_and_saveexec_b64 s[6:7], s[42:43]
	s_cbranch_execz .LBB0_398
	ds_read_b128 v[162:165], v166 offset:5248
.LBB0_398:
	s_or_b64 exec, exec, s[6:7]
	v_mov_b32_e32 v155, 0
	v_mov_b32_e32 v156, 0
	v_mov_b32_e32 v157, 0
	s_and_saveexec_b64 s[6:7], s[90:91]
	s_cbranch_execz .LBB0_400
	ds_read_b128 v[154:157], v166 offset:5376
.LBB0_400:
	s_or_b64 exec, exec, s[6:7]
	v_mov_b32_e32 v168, v188
	v_mov_b32_e32 v169, v188
	v_pk_mul_f32 v[204:205], v[44:45], v[168:169]
	v_pk_mul_f32 v[210:211], v[36:37], v[168:169]
	s_waitcnt lgkmcnt(0)
	v_lshlrev_b32_e32 v168, 16, v162
	v_and_b32_e32 v169, 0xffff0000, v162
	v_lshlrev_b32_e32 v162, 16, v163
	v_and_b32_e32 v163, 0xffff0000, v163
	v_lshlrev_b32_e32 v170, 16, v158
	v_and_b32_e32 v171, 0xffff0000, v158
	v_pk_mul_f32 v[162:163], v[152:153], v[162:163]
	v_lshlrev_b32_e32 v158, 16, v159
	v_and_b32_e32 v159, 0xffff0000, v159
	v_pk_fma_f32 v[158:159], v[148:149], v[158:159], v[162:163]
	v_lshlrev_b32_e32 v162, 16, v155
	v_and_b32_e32 v163, 0xffff0000, v155
	v_pk_fma_f32 v[158:159], v[144:145], v[162:163], v[158:159]
	v_lshlrev_b32_e32 v162, 16, v160
	v_pk_mul_f32 v[158:159], v[204:205], v[158:159]
	v_and_b32_e32 v163, 0xffff0000, v160
	v_cvt_pk_bf16_f32 v155, v158, v159
	v_lshlrev_b32_e32 v158, 16, v164
	v_and_b32_e32 v159, 0xffff0000, v164
	v_pk_mul_f32 v[158:159], v[130:131], v[158:159]
	v_mov_b32_e32 v189, v188
	v_pk_fma_f32 v[158:159], v[134:135], v[162:163], v[158:159]
	v_lshlrev_b32_e32 v162, 16, v156
	v_and_b32_e32 v163, 0xffff0000, v156
	v_pk_mul_f32 v[212:213], v[34:35], v[188:189]
	v_pk_fma_f32 v[158:159], v[138:139], v[162:163], v[158:159]
	v_pk_mul_f32 v[168:169], v[150:151], v[168:169]
	v_pk_mul_f32 v[158:159], v[212:213], v[158:159]
	v_lshlrev_b32_e32 v160, 16, v161
	v_cvt_pk_bf16_f32 v156, v158, v159
	v_lshlrev_b32_e32 v158, 16, v165
	v_and_b32_e32 v159, 0xffff0000, v165
	v_pk_mul_f32 v[158:159], v[132:133], v[158:159]
	v_and_b32_e32 v161, 0xffff0000, v161
	v_pk_fma_f32 v[168:169], v[146:147], v[170:171], v[168:169]
	v_lshlrev_b32_e32 v170, 16, v154
	v_and_b32_e32 v171, 0xffff0000, v154
	v_pk_fma_f32 v[158:159], v[136:137], v[160:161], v[158:159]
	v_lshlrev_b32_e32 v160, 16, v157
	v_and_b32_e32 v161, 0xffff0000, v157
	v_pk_mul_f32 v[208:209], v[42:43], v[188:189]
	v_pk_fma_f32 v[168:169], v[142:143], v[170:171], v[168:169]
	v_pk_fma_f32 v[158:159], v[140:141], v[160:161], v[158:159]
	v_pk_mul_f32 v[168:169], v[208:209], v[168:169]
	v_pk_mul_f32 v[158:159], v[210:211], v[158:159]
	v_cvt_pk_bf16_f32 v154, v168, v169
	v_cvt_pk_bf16_f32 v157, v158, v159
	s_and_saveexec_b64 s[6:7], s[92:93]
	s_xor_b64 s[6:7], exec, s[6:7]
	s_cbranch_execz .LBB0_402
	v_lshl_add_u64 v[158:159], v[206:207], 1, v[224:225]
	global_store_dwordx4 v[158:159], v[154:157], off

; __device__ __forceinline__ unsigned cvt_pk_bf16(float lo, float hi) { f32x2_t v = {lo, hi}; bf16x2_t b = __builtin_convertvector(v, bf16x2_t); return __builtin_bit_cast(unsigned, b); }
;     __device__ __forceinline__ void operator()(const f32x4 (&acc)[2][2][4][2], const Unit& u, int wr, int wc, int fr, int fq) const {
;     ...
;                     for (int m = 0; m < 4; ++m) { const int row = row0 + ai * HALF + m * 16, sq = row & 8191, lr = row & 255; const float r = rr[ai][m];
;                         const bool up_in = lr != 0, dn_in = lr != 255, up_halo = !up_in && sq != 0, dn_halo = !dn_in && sq != 8191;
;                         const bf16_t* up = U + (size_t)row * 1024 + col; const u32x4 z0 = {0u, 0u, 0u, 0u};
;                         const u32x4 uc = *(const u32x4*)up, ul = up_in ? *(const u32x4*)(up - 1024) : z0, ur = dn_in ? *(const u32x4*)(up + 1024) : z0;
;                         const f32x4 b0 = acc[ai][bj][m][0] * r, b1 = acc[ai][bj][m][1] * r;
;                         u32x4 w;
;                         w.x = cvt_pk_bf16(b0[0] * (k0a[0] * bf_lo(ul.x) + k1a[0] * bf_lo(uc.x) + k2a[0] * bf_lo(ur.x)), b0[1] * (k0a[1] * bf_hi(ul.x) + k1a[1] * bf_hi(uc.x) + k2a[1] * bf_hi(ur.x)));
;                         w.y = cvt_pk_bf16(b0[2] * (k0a[2] * bf_lo(ul.y) + k1a[2] * bf_lo(uc.y) + k2a[2] * bf_lo(ur.y)), b0[3] * (k0a[3] * bf_hi(ul.y) + k1a[3] * bf_hi(uc.y) + k2a[3] * bf_hi(ur.y)));
;                         w.z = cvt_pk_bf16(b1[0] * (k0b[0] * bf_lo(ul.z) + k1b[0] * bf_lo(uc.z) + k2b[0] * bf_lo(ur.z)), b1[1] * (k0b[1] * bf_hi(ul.z) + k1b[1] * bf_hi(uc.z) + k2b[1] * bf_hi(ur.z)));
;                         w.w = cvt_pk_bf16(b1[2] * (k0b[2] * bf_lo(ul.w) + k1b[2] * bf_lo(uc.w) + k2b[2] * bf_lo(ur.w)), b1[3] * (k0b[3] * bf_hi(ul.w) + k1b[3] * bf_hi(uc.w) + k2b[3] * bf_hi(ur.w)));
;                         if (up_halo || dn_halo) { const size_t ho = (size_t)(2 * u.pm + (dn_halo ? 1 : 0)) * 1024 + col;
;                             u32x4 bw; bw.x = cvt_pk_bf16(b0[0], b0[1]); bw.y = cvt_pk_bf16(b0[2], b0[3]); bw.z = cvt_pk_bf16(b1[0], b1[1]); bw.w = cvt_pk_bf16(b1[2], b1[3]);
;                             *(u32x4*)(HZ + ho) = w; *(u32x4*)(HBg + ho) = bw; }
;                         else *(u32x4*)(Z + (size_t)row * 1024 + col) = w; }
.LBB0_404:
	s_or_b64 exec, exec, s[6:7]
	v_lshl_add_u64 v[204:205], v[206:207], 1, v[230:231]
	ds_read_b128 v[158:161], v166 offset:6336
	v_mov_b32_e32 v154, 0
	v_mov_b32_e32 v162, 0
	v_mov_b32_e32 v163, 0
	v_mov_b32_e32 v164, 0
	v_mov_b32_e32 v165, 0
	s_and_saveexec_b64 s[6:7], s[94:95]
	s_cbranch_execz .LBB0_406
	ds_read_b128 v[162:165], v166 offset:6272
.LBB0_406:
	s_or_b64 exec, exec, s[6:7]
	v_mov_b32_e32 v155, 0
	v_mov_b32_e32 v156, 0
	v_mov_b32_e32 v157, 0
	s_and_saveexec_b64 s[6:7], s[96:97]
	s_cbranch_execz .LBB0_408
	ds_read_b128 v[154:157], v166 offset:6400
.LBB0_408:
	s_or_b64 exec, exec, s[6:7]
	v_mov_b32_e32 v168, v186
	v_mov_b32_e32 v169, v186
	v_pk_mul_f32 v[204:205], v[28:29], v[168:169]
	v_pk_mul_f32 v[210:211], v[20:21], v[168:169]
	s_waitcnt lgkmcnt(0)
	v_lshlrev_b32_e32 v168, 16, v162
	v_and_b32_e32 v169, 0xffff0000, v162
	v_lshlrev_b32_e32 v162, 16, v163
	v_and_b32_e32 v163, 0xffff0000, v163
	v_lshlrev_b32_e32 v170, 16, v158
	v_and_b32_e32 v171, 0xffff0000, v158
	v_pk_mul_f32 v[162:163], v[152:153], v[162:163]
	v_lshlrev_b32_e32 v158, 16, v159
	v_and_b32_e32 v159, 0xffff0000, v159
	v_pk_fma_f32 v[158:159], v[148:149], v[158:159], v[162:163]
	v_lshlrev_b32_e32 v162, 16, v155
	v_and_b32_e32 v163, 0xffff0000, v155
	v_pk_fma_f32 v[158:159], v[144:145], v[162:163], v[158:159]
	v_lshlrev_b32_e32 v162, 16, v160
	v_pk_mul_f32 v[158:159], v[204:205], v[158:159]
	v_and_b32_e32 v163, 0xffff0000, v160
	v_cvt_pk_bf16_f32 v155, v158, v159
	v_lshlrev_b32_e32 v158, 16, v164
	v_and_b32_e32 v159, 0xffff0000, v164
	v_pk_mul_f32 v[158:159], v[130:131], v[158:159]
	v_mov_b32_e32 v187, v186
	v_pk_fma_f32 v[158:159], v[134:135], v[162:163], v[158:159]
	v_lshlrev_b32_e32 v162, 16, v156
	v_and_b32_e32 v163, 0xffff0000, v156
	v_pk_mul_f32 v[212:213], v[18:19], v[186:187]
	v_pk_fma_f32 v[158:159], v[138:139], v[162:163], v[158:159]
	v_pk_mul_f32 v[168:169], v[150:151], v[168:169]
	v_pk_mul_f32 v[158:159], v[212:213], v[158:159]
	v_lshlrev_b32_e32 v160, 16, v161
	v_cvt_pk_bf16_f32 v156, v158, v159
	v_lshlrev_b32_e32 v158, 16, v165
	v_and_b32_e32 v159, 0xffff0000, v165
	v_pk_mul_f32 v[158:159], v[132:133], v[158:159]
	v_and_b32_e32 v161, 0xffff0000, v161
	v_pk_fma_f32 v[168:169], v[146:147], v[170:171], v[168:169]
	v_lshlrev_b32_e32 v170, 16, v154
	v_and_b32_e32 v171, 0xffff0000, v154
	v_pk_fma_f32 v[158:159], v[136:137], v[160:161], v[158:159]
	v_lshlrev_b32_e32 v160, 16, v157
	v_and_b32_e32 v161, 0xffff0000, v157
	v_pk_mul_f32 v[208:209], v[26:27], v[186:187]
	v_pk_fma_f32 v[168:169], v[142:143], v[170:171], v[168:169]
	v_pk_fma_f32 v[158:159], v[140:141], v[160:161], v[158:159]
	v_pk_mul_f32 v[168:169], v[208:209], v[168:169]
	v_pk_mul_f32 v[158:159], v[210:211], v[158:159]
	v_cvt_pk_bf16_f32 v154, v168, v169
	v_cvt_pk_bf16_f32 v157, v158, v159
	s_and_saveexec_b64 s[6:7], s[88:89]
	s_xor_b64 s[6:7], exec, s[6:7]
	s_cbranch_execz .LBB0_410
	v_lshl_add_u64 v[158:159], v[206:207], 1, v[228:229]
	global_store_dwordx4 v[158:159], v[154:157], off

; __device__ __forceinline__ unsigned cvt_pk_bf16(float lo, float hi) { f32x2_t v = {lo, hi}; bf16x2_t b = __builtin_convertvector(v, bf16x2_t); return __builtin_bit_cast(unsigned, b); }
;     __device__ __forceinline__ void operator()(const f32x4 (&acc)[2][2][4][2], const Unit& u, int wr, int wc, int fr, int fq) const {
;     ...
;                     for (int m = 0; m < 4; ++m) { const int row = row0 + ai * HALF + m * 16, sq = row & 8191, lr = row & 255; const float r = rr[ai][m];
;                         const bool up_in = lr != 0, dn_in = lr != 255, up_halo = !up_in && sq != 0, dn_halo = !dn_in && sq != 8191;
;                         const bf16_t* up = U + (size_t)row * 1024 + col; const u32x4 z0 = {0u, 0u, 0u, 0u};
;                         const u32x4 uc = *(const u32x4*)up, ul = up_in ? *(const u32x4*)(up - 1024) : z0, ur = dn_in ? *(const u32x4*)(up + 1024) : z0;
;                         const f32x4 b0 = acc[ai][bj][m][0] * r, b1 = acc[ai][bj][m][1] * r;
;                         u32x4 w;
;                         w.x = cvt_pk_bf16(b0[0] * (k0a[0] * bf_lo(ul.x) + k1a[0] * bf_lo(uc.x) + k2a[0] * bf_lo(ur.x)), b0[1] * (k0a[1] * bf_hi(ul.x) + k1a[1] * bf_hi(uc.x) + k2a[1] * bf_hi(ur.x)));
;                         w.y = cvt_pk_bf16(b0[2] * (k0a[2] * bf_lo(ul.y) + k1a[2] * bf_lo(uc.y) + k2a[2] * bf_lo(ur.y)), b0[3] * (k0a[3] * bf_hi(ul.y) + k1a[3] * bf_hi(uc.y) + k2a[3] * bf_hi(ur.y)));
;                         w.z = cvt_pk_bf16(b1[0] * (k0b[0] * bf_lo(ul.z) + k1b[0] * bf_lo(uc.z) + k2b[0] * bf_lo(ur.z)), b1[1] * (k0b[1] * bf_hi(ul.z) + k1b[1] * bf_hi(uc.z) + k2b[1] * bf_hi(ur.z)));
;                         w.w = cvt_pk_bf16(b1[2] * (k0b[2] * bf_lo(ul.w) + k1b[2] * bf_lo(uc.w) + k2b[2] * bf_lo(ur.w)), b1[3] * (k0b[3] * bf_hi(ul.w) + k1b[3] * bf_hi(uc.w) + k2b[3] * bf_hi(ur.w)));
;                         if (up_halo || dn_halo) { const size_t ho = (size_t)(2 * u.pm + (dn_halo ? 1 : 0)) * 1024 + col;
;                             u32x4 bw; bw.x = cvt_pk_bf16(b0[0], b0[1]); bw.y = cvt_pk_bf16(b0[2], b0[3]); bw.z = cvt_pk_bf16(b1[0], b1[1]); bw.w = cvt_pk_bf16(b1[2], b1[3]);
;                             *(u32x4*)(HZ + ho) = w; *(u32x4*)(HBg + ho) = bw; }
;                         else *(u32x4*)(Z + (size_t)row * 1024 + col) = w; }
.LBB0_412:
	s_or_b64 exec, exec, s[6:7]
	v_lshl_add_u64 v[204:205], v[206:207], 1, v[232:233]
	ds_read_b128 v[158:161], v166 offset:7360
	v_mov_b32_e32 v154, 0
	v_mov_b32_e32 v162, 0
	v_mov_b32_e32 v163, 0
	v_mov_b32_e32 v164, 0
	v_mov_b32_e32 v165, 0
	s_and_saveexec_b64 s[6:7], s[60:61]
	s_cbranch_execz .LBB0_414
	ds_read_b128 v[162:165], v166 offset:7296
.LBB0_414:
	s_or_b64 exec, exec, s[6:7]
	v_mov_b32_e32 v155, 0
	v_mov_b32_e32 v156, 0
	v_mov_b32_e32 v157, 0
	s_and_saveexec_b64 s[6:7], s[56:57]
	s_cbranch_execz .LBB0_416
	ds_read_b128 v[154:157], v166 offset:7424
.LBB0_416:
	s_or_b64 exec, exec, s[6:7]
	v_mov_b32_e32 v168, v184
	v_mov_b32_e32 v169, v184
	v_pk_mul_f32 v[204:205], v[12:13], v[168:169]
	v_pk_mul_f32 v[210:211], v[4:5], v[168:169]
	s_waitcnt lgkmcnt(0)
	v_lshlrev_b32_e32 v168, 16, v162
	v_and_b32_e32 v169, 0xffff0000, v162
	v_pk_mul_f32 v[150:151], v[150:151], v[168:169]
	v_lshlrev_b32_e32 v168, 16, v158
	v_and_b32_e32 v169, 0xffff0000, v158
	v_pk_fma_f32 v[146:147], v[146:147], v[168:169], v[150:151]
	v_lshlrev_b32_e32 v150, 16, v154
	v_and_b32_e32 v151, 0xffff0000, v154
	v_pk_fma_f32 v[142:143], v[142:143], v[150:151], v[146:147]
	v_lshlrev_b32_e32 v146, 16, v163
	v_and_b32_e32 v147, 0xffff0000, v163
	v_pk_mul_f32 v[146:147], v[152:153], v[146:147]
	v_lshlrev_b32_e32 v150, 16, v159
	v_and_b32_e32 v151, 0xffff0000, v159
	v_mov_b32_e32 v185, v184
	v_pk_fma_f32 v[146:147], v[148:149], v[150:151], v[146:147]
	v_lshlrev_b32_e32 v148, 16, v155
	v_and_b32_e32 v149, 0xffff0000, v155
	v_pk_mul_f32 v[208:209], v[10:11], v[184:185]
	v_pk_fma_f32 v[144:145], v[144:145], v[148:149], v[146:147]
	v_pk_mul_f32 v[142:143], v[208:209], v[142:143]
	v_pk_mul_f32 v[144:145], v[204:205], v[144:145]
	v_cvt_pk_bf16_f32 v142, v142, v143
	v_cvt_pk_bf16_f32 v143, v144, v145
	v_lshlrev_b32_e32 v144, 16, v164
	v_and_b32_e32 v145, 0xffff0000, v164
	v_pk_mul_f32 v[130:131], v[130:131], v[144:145]
	v_lshlrev_b32_e32 v144, 16, v160
	v_and_b32_e32 v145, 0xffff0000, v160
	v_pk_fma_f32 v[130:131], v[134:135], v[144:145], v[130:131]
	v_lshlrev_b32_e32 v134, 16, v156
	v_and_b32_e32 v135, 0xffff0000, v156
	v_pk_mul_f32 v[212:213], v[2:3], v[184:185]
	v_pk_fma_f32 v[130:131], v[138:139], v[134:135], v[130:131]
	s_nop 0
	v_pk_mul_f32 v[130:131], v[212:213], v[130:131]
	s_nop 0
	v_cvt_pk_bf16_f32 v144, v130, v131
	v_lshlrev_b32_e32 v130, 16, v165
	v_and_b32_e32 v131, 0xffff0000, v165
	v_pk_mul_f32 v[130:131], v[132:133], v[130:131]
	v_lshlrev_b32_e32 v132, 16, v161
	v_and_b32_e32 v133, 0xffff0000, v161
	v_pk_fma_f32 v[130:131], v[136:137], v[132:133], v[130:131]
	v_lshlrev_b32_e32 v132, 16, v157
	v_and_b32_e32 v133, 0xffff0000, v157
	v_pk_fma_f32 v[130:131], v[140:141], v[132:133], v[130:131]
	s_nop 0
	v_pk_mul_f32 v[130:131], v[210:211], v[130:131]
	s_nop 0
	v_cvt_pk_bf16_f32 v145, v130, v131
	s_and_saveexec_b64 s[6:7], vcc
	s_xor_b64 s[6:7], exec, s[6:7]
	s_cbranch_execz .LBB0_418
	v_lshl_add_u64 v[130:131], v[206:207], 1, v[202:203]
	global_store_dwordx4 v[130:131], v[142:145], off
